# unrolled GEMM loops without priority toggles and with two LDS waits per MFMA group; out-proj start stagger 14 units
# speedup vs baseline: 1.0071x; 1.0011x over previous
.Lg1_loop:
	ds_read_b128 v[126:129], v217
	ds_read_b128 v[134:137], v221
	ds_read_b128 v[138:141], v221 offset:4096
	ds_read_b128 v[130:133], v217 offset:4096
	s_add_i32 m0, s79, 0x1bf80
	s_waitcnt lgkmcnt(5)
	v_mfma_f32_32x32x16_bf16 v[50:65], v[108:111], v[116:119], 0
	global_load_lds_dwordx4 v144, s[72:73] offset:-1664
	s_add_i32 m0, s79, 0x1df80
	v_mfma_f32_32x32x16_bf16 v[18:33], v[108:111], v[120:123], 0
	global_load_lds_dwordx4 v145, s[72:73] offset:-1664
	s_waitcnt lgkmcnt(4)
	v_mfma_f32_32x32x16_bf16 v[34:49], v[112:115], v[116:119], 0
	v_mfma_f32_32x32x16_bf16 v[2:17], v[112:115], v[120:123], 0
	ds_read_b128 v[108:111], v218
	ds_read_b128 v[116:119], v222
	ds_read_b128 v[120:123], v222 offset:4096
	ds_read_b128 v[112:115], v218 offset:4096
	s_add_i32 m0, s79, 0x1ff80
	s_waitcnt lgkmcnt(5)
	v_mfma_f32_32x32x16_bf16 v[50:65], v[126:129], v[134:137], v[50:65]
	global_load_lds_dwordx4 v144, s[74:75] offset:-1664
	s_add_i32 m0, s79, 0x21f80
	v_mfma_f32_32x32x16_bf16 v[18:33], v[126:129], v[138:141], v[18:33]
	global_load_lds_dwordx4 v145, s[74:75] offset:-1664
	s_waitcnt lgkmcnt(4)
	v_mfma_f32_32x32x16_bf16 v[34:49], v[130:133], v[134:137], v[34:49]
	v_mfma_f32_32x32x16_bf16 v[2:17], v[130:133], v[138:141], v[2:17]
	ds_read_b128 v[126:129], v219
	ds_read_b128 v[134:137], v223
	ds_read_b128 v[138:141], v223 offset:4096
	ds_read_b128 v[130:133], v219 offset:4096
	s_add_i32 m0, s79, 0x23f80
	s_waitcnt lgkmcnt(5)
	v_mfma_f32_32x32x16_bf16 v[50:65], v[108:111], v[116:119], v[50:65]
	global_load_lds_dwordx4 v146, s[74:75] offset:-1664
	s_add_i32 m0, s79, 0x25f80
	v_mfma_f32_32x32x16_bf16 v[18:33], v[108:111], v[120:123], v[18:33]
	global_load_lds_dwordx4 v147, s[74:75] offset:-1664
	s_waitcnt lgkmcnt(4)
	v_mfma_f32_32x32x16_bf16 v[34:49], v[112:115], v[116:119], v[34:49]
	v_mfma_f32_32x32x16_bf16 v[2:17], v[112:115], v[120:123], v[2:17]
	s_waitcnt lgkmcnt(0)
	s_waitcnt vmcnt(6)
	s_barrier
	ds_read_b128 v[108:111], v216 offset:49152
	ds_read_b128 v[116:119], v220 offset:49152
	ds_read_b128 v[120:123], v220 offset:53248
	ds_read_b128 v[112:115], v216 offset:53248
	v_mfma_f32_32x32x16_bf16 v[50:65], v[126:129], v[134:137], v[50:65]
	v_mfma_f32_32x32x16_bf16 v[18:33], v[126:129], v[138:141], v[18:33]
	v_mfma_f32_32x32x16_bf16 v[34:49], v[130:133], v[134:137], v[34:49]
	v_mfma_f32_32x32x16_bf16 v[2:17], v[130:133], v[138:141], v[2:17]
	ds_read_b128 v[126:129], v217 offset:49152
	ds_read_b128 v[134:137], v221 offset:49152
	ds_read_b128 v[138:141], v221 offset:53248
	ds_read_b128 v[130:133], v217 offset:53248
	s_add_i32 m0, s79, 0x700
	s_waitcnt lgkmcnt(5)
	v_mfma_f32_32x32x16_bf16 v[50:65], v[108:111], v[116:119], v[50:65]
	global_load_lds_dwordx4 v144, s[72:73] offset:-1536
	s_add_i32 m0, s79, 0x2700
	v_mfma_f32_32x32x16_bf16 v[18:33], v[108:111], v[120:123], v[18:33]
	global_load_lds_dwordx4 v145, s[72:73] offset:-1536
	s_waitcnt lgkmcnt(4)
	v_mfma_f32_32x32x16_bf16 v[34:49], v[112:115], v[116:119], v[34:49]
	v_mfma_f32_32x32x16_bf16 v[2:17], v[112:115], v[120:123], v[2:17]
	ds_read_b128 v[108:111], v218 offset:49152
	ds_read_b128 v[116:119], v222 offset:49152
	ds_read_b128 v[120:123], v222 offset:53248
	ds_read_b128 v[112:115], v218 offset:53248
	s_add_i32 m0, s79, 0x4700
	s_waitcnt lgkmcnt(5)
	v_mfma_f32_32x32x16_bf16 v[50:65], v[126:129], v[134:137], v[50:65]
	global_load_lds_dwordx4 v144, s[74:75] offset:-1536
	s_add_i32 m0, s79, 0x6700
	v_mfma_f32_32x32x16_bf16 v[18:33], v[126:129], v[138:141], v[18:33]
	global_load_lds_dwordx4 v145, s[74:75] offset:-1536
	s_waitcnt lgkmcnt(4)
	v_mfma_f32_32x32x16_bf16 v[34:49], v[130:133], v[134:137], v[34:49]
	v_mfma_f32_32x32x16_bf16 v[2:17], v[130:133], v[138:141], v[2:17]
	ds_read_b128 v[126:129], v219 offset:49152
	ds_read_b128 v[134:137], v223 offset:49152
	ds_read_b128 v[138:141], v223 offset:53248
	ds_read_b128 v[130:133], v219 offset:53248
	s_add_i32 m0, s79, 0x8700
	s_waitcnt lgkmcnt(5)
	v_mfma_f32_32x32x16_bf16 v[50:65], v[108:111], v[116:119], v[50:65]
	global_load_lds_dwordx4 v146, s[74:75] offset:-1536
	s_add_i32 m0, s79, 0xa700
	v_mfma_f32_32x32x16_bf16 v[18:33], v[108:111], v[120:123], v[18:33]
	global_load_lds_dwordx4 v147, s[74:75] offset:-1536
	s_waitcnt lgkmcnt(4)
	v_mfma_f32_32x32x16_bf16 v[34:49], v[112:115], v[116:119], v[34:49]
	v_mfma_f32_32x32x16_bf16 v[2:17], v[112:115], v[120:123], v[2:17]
	s_waitcnt lgkmcnt(0)
	s_waitcnt vmcnt(6)
	s_barrier
	ds_read_b128 v[108:111], v224
	ds_read_b128 v[116:119], v228
	ds_read_b128 v[120:123], v228 offset:4096
	ds_read_b128 v[112:115], v224 offset:4096
	v_mfma_f32_32x32x16_bf16 v[50:65], v[126:129], v[134:137], v[50:65]
	v_mfma_f32_32x32x16_bf16 v[18:33], v[126:129], v[138:141], v[18:33]
	v_mfma_f32_32x32x16_bf16 v[34:49], v[130:133], v[134:137], v[34:49]
	v_mfma_f32_32x32x16_bf16 v[2:17], v[130:133], v[138:141], v[2:17]
	ds_read_b128 v[126:129], v225
	ds_read_b128 v[134:137], v229
	ds_read_b128 v[138:141], v229 offset:4096
	ds_read_b128 v[130:133], v225 offset:4096
	s_add_i32 m0, s79, 0xc680
	s_waitcnt lgkmcnt(5)
	v_mfma_f32_32x32x16_bf16 v[50:65], v[108:111], v[116:119], v[50:65]
	global_load_lds_dwordx4 v144, s[72:73] offset:-1408
	s_add_i32 m0, s79, 0xe680
	v_mfma_f32_32x32x16_bf16 v[18:33], v[108:111], v[120:123], v[18:33]
	global_load_lds_dwordx4 v145, s[72:73] offset:-1408
	s_waitcnt lgkmcnt(4)
	v_mfma_f32_32x32x16_bf16 v[34:49], v[112:115], v[116:119], v[34:49]
	v_mfma_f32_32x32x16_bf16 v[2:17], v[112:115], v[120:123], v[2:17]
	ds_read_b128 v[108:111], v226
	ds_read_b128 v[116:119], v230
	ds_read_b128 v[120:123], v230 offset:4096
	ds_read_b128 v[112:115], v226 offset:4096
	s_add_i32 m0, s79, 0x10680
	s_waitcnt lgkmcnt(5)
	v_mfma_f32_32x32x16_bf16 v[50:65], v[126:129], v[134:137], v[50:65]
	global_load_lds_dwordx4 v144, s[74:75] offset:-1408
	s_add_i32 m0, s79, 0x12680
	v_mfma_f32_32x32x16_bf16 v[18:33], v[126:129], v[138:141], v[18:33]
	global_load_lds_dwordx4 v145, s[74:75] offset:-1408
	s_waitcnt lgkmcnt(4)
	v_mfma_f32_32x32x16_bf16 v[34:49], v[130:133], v[134:137], v[34:49]
	v_mfma_f32_32x32x16_bf16 v[2:17], v[130:133], v[138:141], v[2:17]
	ds_read_b128 v[126:129], v227
	ds_read_b128 v[134:137], v231
	ds_read_b128 v[138:141], v231 offset:4096
	ds_read_b128 v[130:133], v227 offset:4096
	s_add_i32 m0, s79, 0x14680
	s_waitcnt lgkmcnt(5)
	v_mfma_f32_32x32x16_bf16 v[50:65], v[108:111], v[116:119], v[50:65]
	global_load_lds_dwordx4 v146, s[74:75] offset:-1408
	s_add_i32 m0, s79, 0x16680
	v_mfma_f32_32x32x16_bf16 v[18:33], v[108:111], v[120:123], v[18:33]
	global_load_lds_dwordx4 v147, s[74:75] offset:-1408
	s_waitcnt lgkmcnt(4)
	v_mfma_f32_32x32x16_bf16 v[34:49], v[112:115], v[116:119], v[34:49]
	v_mfma_f32_32x32x16_bf16 v[2:17], v[112:115], v[120:123], v[2:17]
	s_waitcnt lgkmcnt(0)
	s_waitcnt vmcnt(6)
	s_barrier
	ds_read_b128 v[108:111], v216
	ds_read_b128 v[116:119], v220
	ds_read_b128 v[120:123], v220 offset:4096
	ds_read_b128 v[112:115], v216 offset:4096
	v_mfma_f32_32x32x16_bf16 v[50:65], v[126:129], v[134:137], v[50:65]
	v_mfma_f32_32x32x16_bf16 v[18:33], v[126:129], v[138:141], v[18:33]
	v_mfma_f32_32x32x16_bf16 v[34:49], v[130:133], v[134:137], v[34:49]
	v_mfma_f32_32x32x16_bf16 v[2:17], v[130:133], v[138:141], v[2:17]
	ds_read_b128 v[126:129], v217
	ds_read_b128 v[134:137], v221
	ds_read_b128 v[138:141], v221 offset:4096
	ds_read_b128 v[130:133], v217 offset:4096
	s_add_i32 m0, s79, 0x1be00
	s_waitcnt lgkmcnt(5)
	v_mfma_f32_32x32x16_bf16 v[50:65], v[108:111], v[116:119], v[50:65]
	global_load_lds_dwordx4 v144, s[72:73] offset:-1280
	s_add_i32 m0, s79, 0x1de00
	v_mfma_f32_32x32x16_bf16 v[18:33], v[108:111], v[120:123], v[18:33]
	global_load_lds_dwordx4 v145, s[72:73] offset:-1280
	s_waitcnt lgkmcnt(4)
	v_mfma_f32_32x32x16_bf16 v[34:49], v[112:115], v[116:119], v[34:49]
	v_mfma_f32_32x32x16_bf16 v[2:17], v[112:115], v[120:123], v[2:17]
	ds_read_b128 v[108:111], v218
	ds_read_b128 v[116:119], v222
	ds_read_b128 v[120:123], v222 offset:4096
	ds_read_b128 v[112:115], v218 offset:4096
	s_add_i32 m0, s79, 0x1fe00
	s_waitcnt lgkmcnt(5)
	v_mfma_f32_32x32x16_bf16 v[50:65], v[126:129], v[134:137], v[50:65]
	global_load_lds_dwordx4 v144, s[74:75] offset:-1280
	s_add_i32 m0, s79, 0x21e00
	v_mfma_f32_32x32x16_bf16 v[18:33], v[126:129], v[138:141], v[18:33]
	global_load_lds_dwordx4 v145, s[74:75] offset:-1280
	s_waitcnt lgkmcnt(4)
	v_mfma_f32_32x32x16_bf16 v[34:49], v[130:133], v[134:137], v[34:49]
	v_mfma_f32_32x32x16_bf16 v[2:17], v[130:133], v[138:141], v[2:17]
	ds_read_b128 v[126:129], v219
	ds_read_b128 v[134:137], v223
	ds_read_b128 v[138:141], v223 offset:4096
	ds_read_b128 v[130:133], v219 offset:4096
	s_add_i32 m0, s79, 0x23e00
	s_waitcnt lgkmcnt(5)
	v_mfma_f32_32x32x16_bf16 v[50:65], v[108:111], v[116:119], v[50:65]
	global_load_lds_dwordx4 v146, s[74:75] offset:-1280
	s_add_i32 m0, s79, 0x25e00
	v_mfma_f32_32x32x16_bf16 v[18:33], v[108:111], v[120:123], v[18:33]
	global_load_lds_dwordx4 v147, s[74:75] offset:-1280
	s_waitcnt lgkmcnt(4)
	v_mfma_f32_32x32x16_bf16 v[34:49], v[112:115], v[116:119], v[34:49]
	v_mfma_f32_32x32x16_bf16 v[2:17], v[112:115], v[120:123], v[2:17]
	s_waitcnt lgkmcnt(0)
	s_waitcnt vmcnt(6)
	s_barrier
	ds_read_b128 v[108:111], v216 offset:49152
	ds_read_b128 v[116:119], v220 offset:49152
	ds_read_b128 v[120:123], v220 offset:53248
	ds_read_b128 v[112:115], v216 offset:53248
	v_mfma_f32_32x32x16_bf16 v[50:65], v[126:129], v[134:137], v[50:65]
	v_mfma_f32_32x32x16_bf16 v[18:33], v[126:129], v[138:141], v[18:33]
	v_mfma_f32_32x32x16_bf16 v[34:49], v[130:133], v[134:137], v[34:49]
	v_mfma_f32_32x32x16_bf16 v[2:17], v[130:133], v[138:141], v[2:17]
	ds_read_b128 v[126:129], v217 offset:49152
	ds_read_b128 v[134:137], v221 offset:49152
	ds_read_b128 v[138:141], v221 offset:53248
	ds_read_b128 v[130:133], v217 offset:53248
	s_add_i32 m0, s79, 0x580
	s_waitcnt lgkmcnt(5)
	v_mfma_f32_32x32x16_bf16 v[50:65], v[108:111], v[116:119], v[50:65]
	global_load_lds_dwordx4 v144, s[72:73] offset:-1152
	s_add_i32 m0, s79, 0x2580
	v_mfma_f32_32x32x16_bf16 v[18:33], v[108:111], v[120:123], v[18:33]
	global_load_lds_dwordx4 v145, s[72:73] offset:-1152
	s_waitcnt lgkmcnt(4)
	v_mfma_f32_32x32x16_bf16 v[34:49], v[112:115], v[116:119], v[34:49]
	v_mfma_f32_32x32x16_bf16 v[2:17], v[112:115], v[120:123], v[2:17]
	ds_read_b128 v[108:111], v218 offset:49152
	ds_read_b128 v[116:119], v222 offset:49152
	ds_read_b128 v[120:123], v222 offset:53248
	ds_read_b128 v[112:115], v218 offset:53248
	s_add_i32 m0, s79, 0x4580
	s_waitcnt lgkmcnt(5)
	v_mfma_f32_32x32x16_bf16 v[50:65], v[126:129], v[134:137], v[50:65]
	global_load_lds_dwordx4 v144, s[74:75] offset:-1152
	s_add_i32 m0, s79, 0x6580
	v_mfma_f32_32x32x16_bf16 v[18:33], v[126:129], v[138:141], v[18:33]
	global_load_lds_dwordx4 v145, s[74:75] offset:-1152
	s_waitcnt lgkmcnt(4)
	v_mfma_f32_32x32x16_bf16 v[34:49], v[130:133], v[134:137], v[34:49]
	v_mfma_f32_32x32x16_bf16 v[2:17], v[130:133], v[138:141], v[2:17]
	ds_read_b128 v[126:129], v219 offset:49152
	ds_read_b128 v[134:137], v223 offset:49152
	ds_read_b128 v[138:141], v223 offset:53248
	ds_read_b128 v[130:133], v219 offset:53248
	s_add_i32 m0, s79, 0x8580
	s_waitcnt lgkmcnt(5)
	v_mfma_f32_32x32x16_bf16 v[50:65], v[108:111], v[116:119], v[50:65]
	global_load_lds_dwordx4 v146, s[74:75] offset:-1152
	s_add_i32 m0, s79, 0xa580
	v_mfma_f32_32x32x16_bf16 v[18:33], v[108:111], v[120:123], v[18:33]
	global_load_lds_dwordx4 v147, s[74:75] offset:-1152
	s_waitcnt lgkmcnt(4)
	v_mfma_f32_32x32x16_bf16 v[34:49], v[112:115], v[116:119], v[34:49]
	v_mfma_f32_32x32x16_bf16 v[2:17], v[112:115], v[120:123], v[2:17]
	s_waitcnt lgkmcnt(0)
	s_waitcnt vmcnt(6)
	s_barrier
	ds_read_b128 v[108:111], v224
	ds_read_b128 v[116:119], v228
	ds_read_b128 v[120:123], v228 offset:4096
	ds_read_b128 v[112:115], v224 offset:4096
	v_mfma_f32_32x32x16_bf16 v[50:65], v[126:129], v[134:137], v[50:65]
	v_mfma_f32_32x32x16_bf16 v[18:33], v[126:129], v[138:141], v[18:33]
	v_mfma_f32_32x32x16_bf16 v[34:49], v[130:133], v[134:137], v[34:49]
	v_mfma_f32_32x32x16_bf16 v[2:17], v[130:133], v[138:141], v[2:17]
	ds_read_b128 v[126:129], v225
	ds_read_b128 v[134:137], v229
	ds_read_b128 v[138:141], v229 offset:4096
	ds_read_b128 v[130:133], v225 offset:4096
	s_add_i32 m0, s79, 0xc500
	s_waitcnt lgkmcnt(5)
	v_mfma_f32_32x32x16_bf16 v[50:65], v[108:111], v[116:119], v[50:65]
	global_load_lds_dwordx4 v144, s[72:73] offset:-1024
	s_add_i32 m0, s79, 0xe500
	v_mfma_f32_32x32x16_bf16 v[18:33], v[108:111], v[120:123], v[18:33]
	global_load_lds_dwordx4 v145, s[72:73] offset:-1024
	s_waitcnt lgkmcnt(4)
	v_mfma_f32_32x32x16_bf16 v[34:49], v[112:115], v[116:119], v[34:49]
	v_mfma_f32_32x32x16_bf16 v[2:17], v[112:115], v[120:123], v[2:17]
	ds_read_b128 v[108:111], v226
	ds_read_b128 v[116:119], v230
	ds_read_b128 v[120:123], v230 offset:4096
	ds_read_b128 v[112:115], v226 offset:4096
	s_add_i32 m0, s79, 0x10500
	s_waitcnt lgkmcnt(5)
	v_mfma_f32_32x32x16_bf16 v[50:65], v[126:129], v[134:137], v[50:65]
	global_load_lds_dwordx4 v144, s[74:75] offset:-1024
	s_add_i32 m0, s79, 0x12500
	v_mfma_f32_32x32x16_bf16 v[18:33], v[126:129], v[138:141], v[18:33]
	global_load_lds_dwordx4 v145, s[74:75] offset:-1024
	s_waitcnt lgkmcnt(4)
	v_mfma_f32_32x32x16_bf16 v[34:49], v[130:133], v[134:137], v[34:49]
	v_mfma_f32_32x32x16_bf16 v[2:17], v[130:133], v[138:141], v[2:17]
	ds_read_b128 v[126:129], v227
	ds_read_b128 v[134:137], v231
	ds_read_b128 v[138:141], v231 offset:4096
	ds_read_b128 v[130:133], v227 offset:4096
	s_add_i32 m0, s79, 0x14500
	s_waitcnt lgkmcnt(5)
	v_mfma_f32_32x32x16_bf16 v[50:65], v[108:111], v[116:119], v[50:65]
	global_load_lds_dwordx4 v146, s[74:75] offset:-1024
	s_add_i32 m0, s79, 0x16500
	v_mfma_f32_32x32x16_bf16 v[18:33], v[108:111], v[120:123], v[18:33]
	global_load_lds_dwordx4 v147, s[74:75] offset:-1024
	s_waitcnt lgkmcnt(4)
	v_mfma_f32_32x32x16_bf16 v[34:49], v[112:115], v[116:119], v[34:49]
	v_mfma_f32_32x32x16_bf16 v[2:17], v[112:115], v[120:123], v[2:17]
	s_waitcnt lgkmcnt(0)
	s_waitcnt vmcnt(6)
	s_barrier
	ds_read_b128 v[108:111], v216
	ds_read_b128 v[116:119], v220
	ds_read_b128 v[120:123], v220 offset:4096
	ds_read_b128 v[112:115], v216 offset:4096
	v_mfma_f32_32x32x16_bf16 v[50:65], v[126:129], v[134:137], v[50:65]
	v_mfma_f32_32x32x16_bf16 v[18:33], v[126:129], v[138:141], v[18:33]
	v_mfma_f32_32x32x16_bf16 v[34:49], v[130:133], v[134:137], v[34:49]
	v_mfma_f32_32x32x16_bf16 v[2:17], v[130:133], v[138:141], v[2:17]
	ds_read_b128 v[126:129], v217
	ds_read_b128 v[134:137], v221
	ds_read_b128 v[138:141], v221 offset:4096
	ds_read_b128 v[130:133], v217 offset:4096
	s_add_i32 m0, s79, 0x1bc80
	s_waitcnt lgkmcnt(5)
	v_mfma_f32_32x32x16_bf16 v[50:65], v[108:111], v[116:119], v[50:65]
	global_load_lds_dwordx4 v144, s[72:73] offset:-896
	s_add_i32 m0, s79, 0x1dc80
	v_mfma_f32_32x32x16_bf16 v[18:33], v[108:111], v[120:123], v[18:33]
	global_load_lds_dwordx4 v145, s[72:73] offset:-896
	s_waitcnt lgkmcnt(4)
	v_mfma_f32_32x32x16_bf16 v[34:49], v[112:115], v[116:119], v[34:49]
	v_mfma_f32_32x32x16_bf16 v[2:17], v[112:115], v[120:123], v[2:17]
	ds_read_b128 v[108:111], v218
	ds_read_b128 v[116:119], v222
	ds_read_b128 v[120:123], v222 offset:4096
	ds_read_b128 v[112:115], v218 offset:4096
	s_add_i32 m0, s79, 0x1fc80
	s_waitcnt lgkmcnt(5)
	v_mfma_f32_32x32x16_bf16 v[50:65], v[126:129], v[134:137], v[50:65]
	global_load_lds_dwordx4 v144, s[74:75] offset:-896
	s_add_i32 m0, s79, 0x21c80
	v_mfma_f32_32x32x16_bf16 v[18:33], v[126:129], v[138:141], v[18:33]
	global_load_lds_dwordx4 v145, s[74:75] offset:-896
	s_waitcnt lgkmcnt(4)
	v_mfma_f32_32x32x16_bf16 v[34:49], v[130:133], v[134:137], v[34:49]
	v_mfma_f32_32x32x16_bf16 v[2:17], v[130:133], v[138:141], v[2:17]
	ds_read_b128 v[126:129], v219
	ds_read_b128 v[134:137], v223
	ds_read_b128 v[138:141], v223 offset:4096
	ds_read_b128 v[130:133], v219 offset:4096
	s_add_i32 m0, s79, 0x23c80
	s_waitcnt lgkmcnt(5)
	v_mfma_f32_32x32x16_bf16 v[50:65], v[108:111], v[116:119], v[50:65]
	global_load_lds_dwordx4 v146, s[74:75] offset:-896
	s_add_i32 m0, s79, 0x25c80
	v_mfma_f32_32x32x16_bf16 v[18:33], v[108:111], v[120:123], v[18:33]
	global_load_lds_dwordx4 v147, s[74:75] offset:-896
	s_waitcnt lgkmcnt(4)
	v_mfma_f32_32x32x16_bf16 v[34:49], v[112:115], v[116:119], v[34:49]
	v_mfma_f32_32x32x16_bf16 v[2:17], v[112:115], v[120:123], v[2:17]
	s_waitcnt lgkmcnt(0)
	s_waitcnt vmcnt(6)
	s_barrier
	ds_read_b128 v[108:111], v216 offset:49152
	ds_read_b128 v[116:119], v220 offset:49152
	ds_read_b128 v[120:123], v220 offset:53248
	ds_read_b128 v[112:115], v216 offset:53248
	v_mfma_f32_32x32x16_bf16 v[50:65], v[126:129], v[134:137], v[50:65]
	v_mfma_f32_32x32x16_bf16 v[18:33], v[126:129], v[138:141], v[18:33]
	v_mfma_f32_32x32x16_bf16 v[34:49], v[130:133], v[134:137], v[34:49]
	v_mfma_f32_32x32x16_bf16 v[2:17], v[130:133], v[138:141], v[2:17]
	ds_read_b128 v[126:129], v217 offset:49152
	ds_read_b128 v[134:137], v221 offset:49152
	ds_read_b128 v[138:141], v221 offset:53248
	ds_read_b128 v[130:133], v217 offset:53248
	s_add_i32 m0, s79, 0x400
	s_waitcnt lgkmcnt(5)
	v_mfma_f32_32x32x16_bf16 v[50:65], v[108:111], v[116:119], v[50:65]
	global_load_lds_dwordx4 v144, s[72:73] offset:-768
	s_add_i32 m0, s79, 0x2400
	v_mfma_f32_32x32x16_bf16 v[18:33], v[108:111], v[120:123], v[18:33]
	global_load_lds_dwordx4 v145, s[72:73] offset:-768
	s_waitcnt lgkmcnt(4)
	v_mfma_f32_32x32x16_bf16 v[34:49], v[112:115], v[116:119], v[34:49]
	v_mfma_f32_32x32x16_bf16 v[2:17], v[112:115], v[120:123], v[2:17]
	ds_read_b128 v[108:111], v218 offset:49152
	ds_read_b128 v[116:119], v222 offset:49152
	ds_read_b128 v[120:123], v222 offset:53248
	ds_read_b128 v[112:115], v218 offset:53248
	s_add_i32 m0, s79, 0x4400
	s_waitcnt lgkmcnt(5)
	v_mfma_f32_32x32x16_bf16 v[50:65], v[126:129], v[134:137], v[50:65]
	global_load_lds_dwordx4 v144, s[74:75] offset:-768
	s_add_i32 m0, s79, 0x6400
	v_mfma_f32_32x32x16_bf16 v[18:33], v[126:129], v[138:141], v[18:33]
	global_load_lds_dwordx4 v145, s[74:75] offset:-768
	s_waitcnt lgkmcnt(4)
	v_mfma_f32_32x32x16_bf16 v[34:49], v[130:133], v[134:137], v[34:49]
	v_mfma_f32_32x32x16_bf16 v[2:17], v[130:133], v[138:141], v[2:17]
	ds_read_b128 v[126:129], v219 offset:49152
	ds_read_b128 v[134:137], v223 offset:49152
	ds_read_b128 v[138:141], v223 offset:53248
	ds_read_b128 v[130:133], v219 offset:53248
	s_add_i32 m0, s79, 0x8400
	s_waitcnt lgkmcnt(5)
	v_mfma_f32_32x32x16_bf16 v[50:65], v[108:111], v[116:119], v[50:65]
	global_load_lds_dwordx4 v146, s[74:75] offset:-768
	s_add_i32 m0, s79, 0xa400
	v_mfma_f32_32x32x16_bf16 v[18:33], v[108:111], v[120:123], v[18:33]
	global_load_lds_dwordx4 v147, s[74:75] offset:-768
	s_waitcnt lgkmcnt(4)
	v_mfma_f32_32x32x16_bf16 v[34:49], v[112:115], v[116:119], v[34:49]
	v_mfma_f32_32x32x16_bf16 v[2:17], v[112:115], v[120:123], v[2:17]
	s_waitcnt lgkmcnt(0)
	s_waitcnt vmcnt(6)
	s_barrier
	ds_read_b128 v[108:111], v224
	ds_read_b128 v[116:119], v228
	ds_read_b128 v[120:123], v228 offset:4096
	ds_read_b128 v[112:115], v224 offset:4096
	v_mfma_f32_32x32x16_bf16 v[50:65], v[126:129], v[134:137], v[50:65]
	v_mfma_f32_32x32x16_bf16 v[18:33], v[126:129], v[138:141], v[18:33]
	v_mfma_f32_32x32x16_bf16 v[34:49], v[130:133], v[134:137], v[34:49]
	v_mfma_f32_32x32x16_bf16 v[2:17], v[130:133], v[138:141], v[2:17]
	ds_read_b128 v[126:129], v225
	ds_read_b128 v[134:137], v229
	ds_read_b128 v[138:141], v229 offset:4096
	ds_read_b128 v[130:133], v225 offset:4096
	s_add_i32 m0, s79, 0xc380
	s_waitcnt lgkmcnt(5)
	v_mfma_f32_32x32x16_bf16 v[50:65], v[108:111], v[116:119], v[50:65]
	global_load_lds_dwordx4 v144, s[72:73] offset:-640
	s_add_i32 m0, s79, 0xe380
	v_mfma_f32_32x32x16_bf16 v[18:33], v[108:111], v[120:123], v[18:33]
	global_load_lds_dwordx4 v145, s[72:73] offset:-640
	s_waitcnt lgkmcnt(4)
	v_mfma_f32_32x32x16_bf16 v[34:49], v[112:115], v[116:119], v[34:49]
	v_mfma_f32_32x32x16_bf16 v[2:17], v[112:115], v[120:123], v[2:17]
	ds_read_b128 v[108:111], v226
	ds_read_b128 v[116:119], v230
	ds_read_b128 v[120:123], v230 offset:4096
	ds_read_b128 v[112:115], v226 offset:4096
	s_add_i32 m0, s79, 0x10380
	s_waitcnt lgkmcnt(5)
	v_mfma_f32_32x32x16_bf16 v[50:65], v[126:129], v[134:137], v[50:65]
	global_load_lds_dwordx4 v144, s[74:75] offset:-640
	s_add_i32 m0, s79, 0x12380
	v_mfma_f32_32x32x16_bf16 v[18:33], v[126:129], v[138:141], v[18:33]
	global_load_lds_dwordx4 v145, s[74:75] offset:-640
	s_waitcnt lgkmcnt(4)
	v_mfma_f32_32x32x16_bf16 v[34:49], v[130:133], v[134:137], v[34:49]
	v_mfma_f32_32x32x16_bf16 v[2:17], v[130:133], v[138:141], v[2:17]
	ds_read_b128 v[126:129], v227
	ds_read_b128 v[134:137], v231
	ds_read_b128 v[138:141], v231 offset:4096
	ds_read_b128 v[130:133], v227 offset:4096
	s_add_i32 m0, s79, 0x14380
	s_waitcnt lgkmcnt(5)
	v_mfma_f32_32x32x16_bf16 v[50:65], v[108:111], v[116:119], v[50:65]
	global_load_lds_dwordx4 v146, s[74:75] offset:-640
	s_add_i32 m0, s79, 0x16380
	v_mfma_f32_32x32x16_bf16 v[18:33], v[108:111], v[120:123], v[18:33]
	global_load_lds_dwordx4 v147, s[74:75] offset:-640
	s_waitcnt lgkmcnt(4)
	v_mfma_f32_32x32x16_bf16 v[34:49], v[112:115], v[116:119], v[34:49]
	v_mfma_f32_32x32x16_bf16 v[2:17], v[112:115], v[120:123], v[2:17]
	s_waitcnt lgkmcnt(0)
	s_waitcnt vmcnt(6)
	s_barrier
	ds_read_b128 v[108:111], v216
	ds_read_b128 v[116:119], v220
	ds_read_b128 v[120:123], v220 offset:4096
	ds_read_b128 v[112:115], v216 offset:4096
	v_mfma_f32_32x32x16_bf16 v[50:65], v[126:129], v[134:137], v[50:65]
	v_mfma_f32_32x32x16_bf16 v[18:33], v[126:129], v[138:141], v[18:33]
	v_mfma_f32_32x32x16_bf16 v[34:49], v[130:133], v[134:137], v[34:49]
	v_mfma_f32_32x32x16_bf16 v[2:17], v[130:133], v[138:141], v[2:17]
	ds_read_b128 v[126:129], v217
	ds_read_b128 v[134:137], v221
	ds_read_b128 v[138:141], v221 offset:4096
	ds_read_b128 v[130:133], v217 offset:4096
	s_add_i32 m0, s79, 0x1bb00
	s_waitcnt lgkmcnt(5)
	v_mfma_f32_32x32x16_bf16 v[50:65], v[108:111], v[116:119], v[50:65]
	global_load_lds_dwordx4 v144, s[72:73] offset:-512
	s_add_i32 m0, s79, 0x1db00
	v_mfma_f32_32x32x16_bf16 v[18:33], v[108:111], v[120:123], v[18:33]
	global_load_lds_dwordx4 v145, s[72:73] offset:-512
	s_waitcnt lgkmcnt(4)
	v_mfma_f32_32x32x16_bf16 v[34:49], v[112:115], v[116:119], v[34:49]
	v_mfma_f32_32x32x16_bf16 v[2:17], v[112:115], v[120:123], v[2:17]
	ds_read_b128 v[108:111], v218
	ds_read_b128 v[116:119], v222
	ds_read_b128 v[120:123], v222 offset:4096
	ds_read_b128 v[112:115], v218 offset:4096
	s_add_i32 m0, s79, 0x1fb00
	s_waitcnt lgkmcnt(5)
	v_mfma_f32_32x32x16_bf16 v[50:65], v[126:129], v[134:137], v[50:65]
	global_load_lds_dwordx4 v144, s[74:75] offset:-512
	s_add_i32 m0, s79, 0x21b00
	v_mfma_f32_32x32x16_bf16 v[18:33], v[126:129], v[138:141], v[18:33]
	global_load_lds_dwordx4 v145, s[74:75] offset:-512
	s_waitcnt lgkmcnt(4)
	v_mfma_f32_32x32x16_bf16 v[34:49], v[130:133], v[134:137], v[34:49]
	v_mfma_f32_32x32x16_bf16 v[2:17], v[130:133], v[138:141], v[2:17]
	ds_read_b128 v[126:129], v219
	ds_read_b128 v[134:137], v223
	ds_read_b128 v[138:141], v223 offset:4096
	ds_read_b128 v[130:133], v219 offset:4096
	s_add_i32 m0, s79, 0x23b00
	s_waitcnt lgkmcnt(5)
	v_mfma_f32_32x32x16_bf16 v[50:65], v[108:111], v[116:119], v[50:65]
	global_load_lds_dwordx4 v146, s[74:75] offset:-512
	s_add_i32 m0, s79, 0x25b00
	v_mfma_f32_32x32x16_bf16 v[18:33], v[108:111], v[120:123], v[18:33]
	global_load_lds_dwordx4 v147, s[74:75] offset:-512
	s_waitcnt lgkmcnt(4)
	v_mfma_f32_32x32x16_bf16 v[34:49], v[112:115], v[116:119], v[34:49]
	v_mfma_f32_32x32x16_bf16 v[2:17], v[112:115], v[120:123], v[2:17]
	s_waitcnt lgkmcnt(0)
	s_waitcnt vmcnt(6)
	s_barrier
	ds_read_b128 v[108:111], v216 offset:49152
	ds_read_b128 v[116:119], v220 offset:49152
	ds_read_b128 v[120:123], v220 offset:53248
	ds_read_b128 v[112:115], v216 offset:53248
	v_mfma_f32_32x32x16_bf16 v[50:65], v[126:129], v[134:137], v[50:65]
	v_mfma_f32_32x32x16_bf16 v[18:33], v[126:129], v[138:141], v[18:33]
	v_mfma_f32_32x32x16_bf16 v[34:49], v[130:133], v[134:137], v[34:49]
	v_mfma_f32_32x32x16_bf16 v[2:17], v[130:133], v[138:141], v[2:17]
	ds_read_b128 v[126:129], v217 offset:49152
	ds_read_b128 v[134:137], v221 offset:49152
	ds_read_b128 v[138:141], v221 offset:53248
	ds_read_b128 v[130:133], v217 offset:53248
	s_add_i32 m0, s79, 0x280
	s_waitcnt lgkmcnt(5)
	v_mfma_f32_32x32x16_bf16 v[50:65], v[108:111], v[116:119], v[50:65]
	global_load_lds_dwordx4 v144, s[72:73] offset:-384
	s_add_i32 m0, s79, 0x2280
	v_mfma_f32_32x32x16_bf16 v[18:33], v[108:111], v[120:123], v[18:33]
	global_load_lds_dwordx4 v145, s[72:73] offset:-384
	s_waitcnt lgkmcnt(4)
	v_mfma_f32_32x32x16_bf16 v[34:49], v[112:115], v[116:119], v[34:49]
	v_mfma_f32_32x32x16_bf16 v[2:17], v[112:115], v[120:123], v[2:17]
	ds_read_b128 v[108:111], v218 offset:49152
	ds_read_b128 v[116:119], v222 offset:49152
	ds_read_b128 v[120:123], v222 offset:53248
	ds_read_b128 v[112:115], v218 offset:53248
	s_add_i32 m0, s79, 0x4280
	s_waitcnt lgkmcnt(5)
	v_mfma_f32_32x32x16_bf16 v[50:65], v[126:129], v[134:137], v[50:65]
	global_load_lds_dwordx4 v144, s[74:75] offset:-384
	s_add_i32 m0, s79, 0x6280
	v_mfma_f32_32x32x16_bf16 v[18:33], v[126:129], v[138:141], v[18:33]
	global_load_lds_dwordx4 v145, s[74:75] offset:-384
	s_waitcnt lgkmcnt(4)
	v_mfma_f32_32x32x16_bf16 v[34:49], v[130:133], v[134:137], v[34:49]
	v_mfma_f32_32x32x16_bf16 v[2:17], v[130:133], v[138:141], v[2:17]
	ds_read_b128 v[126:129], v219 offset:49152
	ds_read_b128 v[134:137], v223 offset:49152
	ds_read_b128 v[138:141], v223 offset:53248
	ds_read_b128 v[130:133], v219 offset:53248
	s_add_i32 m0, s79, 0x8280
	s_waitcnt lgkmcnt(5)
	v_mfma_f32_32x32x16_bf16 v[50:65], v[108:111], v[116:119], v[50:65]
	global_load_lds_dwordx4 v146, s[74:75] offset:-384
	s_add_i32 m0, s79, 0xa280
	v_mfma_f32_32x32x16_bf16 v[18:33], v[108:111], v[120:123], v[18:33]
	global_load_lds_dwordx4 v147, s[74:75] offset:-384
	s_waitcnt lgkmcnt(4)
	v_mfma_f32_32x32x16_bf16 v[34:49], v[112:115], v[116:119], v[34:49]
	v_mfma_f32_32x32x16_bf16 v[2:17], v[112:115], v[120:123], v[2:17]
	s_waitcnt lgkmcnt(0)
	s_waitcnt vmcnt(6)
	s_barrier
	ds_read_b128 v[108:111], v224
	ds_read_b128 v[116:119], v228
	ds_read_b128 v[120:123], v228 offset:4096
	ds_read_b128 v[112:115], v224 offset:4096
	v_mfma_f32_32x32x16_bf16 v[50:65], v[126:129], v[134:137], v[50:65]
	v_mfma_f32_32x32x16_bf16 v[18:33], v[126:129], v[138:141], v[18:33]
	v_mfma_f32_32x32x16_bf16 v[34:49], v[130:133], v[134:137], v[34:49]
	v_mfma_f32_32x32x16_bf16 v[2:17], v[130:133], v[138:141], v[2:17]
	ds_read_b128 v[126:129], v225
	ds_read_b128 v[134:137], v229
	ds_read_b128 v[138:141], v229 offset:4096
	ds_read_b128 v[130:133], v225 offset:4096
	s_add_i32 m0, s79, 0xc200
	s_waitcnt lgkmcnt(5)
	v_mfma_f32_32x32x16_bf16 v[50:65], v[108:111], v[116:119], v[50:65]
	global_load_lds_dwordx4 v144, s[72:73] offset:-256
	s_add_i32 m0, s79, 0xe200
	v_mfma_f32_32x32x16_bf16 v[18:33], v[108:111], v[120:123], v[18:33]
	global_load_lds_dwordx4 v145, s[72:73] offset:-256
	s_waitcnt lgkmcnt(4)
	v_mfma_f32_32x32x16_bf16 v[34:49], v[112:115], v[116:119], v[34:49]
	v_mfma_f32_32x32x16_bf16 v[2:17], v[112:115], v[120:123], v[2:17]
	ds_read_b128 v[108:111], v226
	ds_read_b128 v[116:119], v230
	ds_read_b128 v[120:123], v230 offset:4096
	ds_read_b128 v[112:115], v226 offset:4096
	s_add_i32 m0, s79, 0x10200
	s_waitcnt lgkmcnt(5)
	v_mfma_f32_32x32x16_bf16 v[50:65], v[126:129], v[134:137], v[50:65]
	global_load_lds_dwordx4 v144, s[74:75] offset:-256
	s_add_i32 m0, s79, 0x12200
	v_mfma_f32_32x32x16_bf16 v[18:33], v[126:129], v[138:141], v[18:33]
	global_load_lds_dwordx4 v145, s[74:75] offset:-256
	s_waitcnt lgkmcnt(4)
	v_mfma_f32_32x32x16_bf16 v[34:49], v[130:133], v[134:137], v[34:49]
	v_mfma_f32_32x32x16_bf16 v[2:17], v[130:133], v[138:141], v[2:17]
	ds_read_b128 v[126:129], v227
	ds_read_b128 v[134:137], v231
	ds_read_b128 v[138:141], v231 offset:4096
	ds_read_b128 v[130:133], v227 offset:4096
	s_add_i32 m0, s79, 0x14200
	s_waitcnt lgkmcnt(5)
	v_mfma_f32_32x32x16_bf16 v[50:65], v[108:111], v[116:119], v[50:65]
	global_load_lds_dwordx4 v146, s[74:75] offset:-256
	s_add_i32 m0, s79, 0x16200
	v_mfma_f32_32x32x16_bf16 v[18:33], v[108:111], v[120:123], v[18:33]
	global_load_lds_dwordx4 v147, s[74:75] offset:-256
	s_waitcnt lgkmcnt(4)
	v_mfma_f32_32x32x16_bf16 v[34:49], v[112:115], v[116:119], v[34:49]
	v_mfma_f32_32x32x16_bf16 v[2:17], v[112:115], v[120:123], v[2:17]
	s_waitcnt lgkmcnt(0)
	s_waitcnt vmcnt(6)
	s_barrier
	ds_read_b128 v[108:111], v216
	ds_read_b128 v[116:119], v220
	ds_read_b128 v[120:123], v220 offset:4096
	ds_read_b128 v[112:115], v216 offset:4096
	v_mfma_f32_32x32x16_bf16 v[50:65], v[126:129], v[134:137], v[50:65]
	v_mfma_f32_32x32x16_bf16 v[18:33], v[126:129], v[138:141], v[18:33]
	v_mfma_f32_32x32x16_bf16 v[34:49], v[130:133], v[134:137], v[34:49]
	v_mfma_f32_32x32x16_bf16 v[2:17], v[130:133], v[138:141], v[2:17]
	ds_read_b128 v[126:129], v217
	ds_read_b128 v[134:137], v221
	ds_read_b128 v[138:141], v221 offset:4096
	ds_read_b128 v[130:133], v217 offset:4096
	s_add_i32 m0, s79, 0x1b980
	s_waitcnt lgkmcnt(5)
	v_mfma_f32_32x32x16_bf16 v[50:65], v[108:111], v[116:119], v[50:65]
	global_load_lds_dwordx4 v144, s[72:73] offset:-128
	s_add_i32 m0, s79, 0x1d980
	v_mfma_f32_32x32x16_bf16 v[18:33], v[108:111], v[120:123], v[18:33]
	global_load_lds_dwordx4 v145, s[72:73] offset:-128
	s_waitcnt lgkmcnt(4)
	v_mfma_f32_32x32x16_bf16 v[34:49], v[112:115], v[116:119], v[34:49]
	v_mfma_f32_32x32x16_bf16 v[2:17], v[112:115], v[120:123], v[2:17]
	ds_read_b128 v[108:111], v218
	ds_read_b128 v[116:119], v222
	ds_read_b128 v[120:123], v222 offset:4096
	ds_read_b128 v[112:115], v218 offset:4096
	s_add_i32 m0, s79, 0x1f980
	s_waitcnt lgkmcnt(5)
	v_mfma_f32_32x32x16_bf16 v[50:65], v[126:129], v[134:137], v[50:65]
	global_load_lds_dwordx4 v144, s[74:75] offset:-128
	s_add_i32 m0, s79, 0x21980
	v_mfma_f32_32x32x16_bf16 v[18:33], v[126:129], v[138:141], v[18:33]
	global_load_lds_dwordx4 v145, s[74:75] offset:-128
	s_waitcnt lgkmcnt(4)
	v_mfma_f32_32x32x16_bf16 v[34:49], v[130:133], v[134:137], v[34:49]
	v_mfma_f32_32x32x16_bf16 v[2:17], v[130:133], v[138:141], v[2:17]
	ds_read_b128 v[126:129], v219
	ds_read_b128 v[134:137], v223
	ds_read_b128 v[138:141], v223 offset:4096
	ds_read_b128 v[130:133], v219 offset:4096
	s_add_i32 m0, s79, 0x23980
	s_waitcnt lgkmcnt(5)
	v_mfma_f32_32x32x16_bf16 v[50:65], v[108:111], v[116:119], v[50:65]
	global_load_lds_dwordx4 v146, s[74:75] offset:-128
	s_add_i32 m0, s79, 0x25980
	v_mfma_f32_32x32x16_bf16 v[18:33], v[108:111], v[120:123], v[18:33]
	global_load_lds_dwordx4 v147, s[74:75] offset:-128
	s_waitcnt lgkmcnt(4)
	v_mfma_f32_32x32x16_bf16 v[34:49], v[112:115], v[116:119], v[34:49]
	v_mfma_f32_32x32x16_bf16 v[2:17], v[112:115], v[120:123], v[2:17]
	s_waitcnt lgkmcnt(0)
	s_waitcnt vmcnt(6)
	s_barrier
	ds_read_b128 v[108:111], v216 offset:49152
	ds_read_b128 v[116:119], v220 offset:49152
	ds_read_b128 v[120:123], v220 offset:53248
	ds_read_b128 v[112:115], v216 offset:53248
	v_mfma_f32_32x32x16_bf16 v[50:65], v[126:129], v[134:137], v[50:65]
	v_mfma_f32_32x32x16_bf16 v[18:33], v[126:129], v[138:141], v[18:33]
	v_mfma_f32_32x32x16_bf16 v[34:49], v[130:133], v[134:137], v[34:49]
	v_mfma_f32_32x32x16_bf16 v[2:17], v[130:133], v[138:141], v[2:17]
	ds_read_b128 v[126:129], v217 offset:49152
	ds_read_b128 v[134:137], v221 offset:49152
	ds_read_b128 v[138:141], v221 offset:53248
	ds_read_b128 v[130:133], v217 offset:53248
	s_add_i32 m0, s79, 0x100
	s_waitcnt lgkmcnt(5)
	v_mfma_f32_32x32x16_bf16 v[50:65], v[108:111], v[116:119], v[50:65]
	global_load_lds_dwordx4 v144, s[72:73]
	s_add_i32 m0, s79, 0x2100
	v_mfma_f32_32x32x16_bf16 v[18:33], v[108:111], v[120:123], v[18:33]
	global_load_lds_dwordx4 v145, s[72:73]
	s_waitcnt lgkmcnt(4)
	v_mfma_f32_32x32x16_bf16 v[34:49], v[112:115], v[116:119], v[34:49]
	v_mfma_f32_32x32x16_bf16 v[2:17], v[112:115], v[120:123], v[2:17]
	ds_read_b128 v[108:111], v218 offset:49152
	ds_read_b128 v[116:119], v222 offset:49152
	ds_read_b128 v[120:123], v222 offset:53248
	ds_read_b128 v[112:115], v218 offset:53248
	s_add_i32 m0, s79, 0x4100
	s_waitcnt lgkmcnt(5)
	v_mfma_f32_32x32x16_bf16 v[50:65], v[126:129], v[134:137], v[50:65]
	global_load_lds_dwordx4 v144, s[74:75]
	s_add_i32 m0, s79, 0x6100
	v_mfma_f32_32x32x16_bf16 v[18:33], v[126:129], v[138:141], v[18:33]
	global_load_lds_dwordx4 v145, s[74:75]
	s_waitcnt lgkmcnt(4)
	v_mfma_f32_32x32x16_bf16 v[34:49], v[130:133], v[134:137], v[34:49]
	v_mfma_f32_32x32x16_bf16 v[2:17], v[130:133], v[138:141], v[2:17]
	ds_read_b128 v[126:129], v219 offset:49152
	ds_read_b128 v[134:137], v223 offset:49152
	ds_read_b128 v[138:141], v223 offset:53248
	ds_read_b128 v[130:133], v219 offset:53248
	s_add_i32 m0, s79, 0x8100
	s_waitcnt lgkmcnt(5)
	v_mfma_f32_32x32x16_bf16 v[50:65], v[108:111], v[116:119], v[50:65]
	global_load_lds_dwordx4 v146, s[74:75]
	s_add_i32 m0, s79, 0xa100
	v_mfma_f32_32x32x16_bf16 v[18:33], v[108:111], v[120:123], v[18:33]
	global_load_lds_dwordx4 v147, s[74:75]
	s_waitcnt lgkmcnt(4)
	v_mfma_f32_32x32x16_bf16 v[34:49], v[112:115], v[116:119], v[34:49]
	v_mfma_f32_32x32x16_bf16 v[2:17], v[112:115], v[120:123], v[2:17]
	s_waitcnt lgkmcnt(0)
	s_waitcnt vmcnt(6)
	s_barrier
	ds_read_b128 v[108:111], v224
	ds_read_b128 v[116:119], v228
	ds_read_b128 v[120:123], v228 offset:4096
	ds_read_b128 v[112:115], v224 offset:4096
	v_mfma_f32_32x32x16_bf16 v[50:65], v[126:129], v[134:137], v[50:65]
	v_mfma_f32_32x32x16_bf16 v[18:33], v[126:129], v[138:141], v[18:33]
	v_mfma_f32_32x32x16_bf16 v[34:49], v[130:133], v[134:137], v[34:49]
	v_mfma_f32_32x32x16_bf16 v[2:17], v[130:133], v[138:141], v[2:17]
	ds_read_b128 v[126:129], v225
	ds_read_b128 v[134:137], v229
	ds_read_b128 v[138:141], v229 offset:4096
	ds_read_b128 v[130:133], v225 offset:4096
	s_waitcnt lgkmcnt(5)
	v_mfma_f32_32x32x16_bf16 v[50:65], v[108:111], v[116:119], v[50:65]
	v_mfma_f32_32x32x16_bf16 v[18:33], v[108:111], v[120:123], v[18:33]
	s_waitcnt lgkmcnt(4)
	v_mfma_f32_32x32x16_bf16 v[34:49], v[112:115], v[116:119], v[34:49]
	v_mfma_f32_32x32x16_bf16 v[2:17], v[112:115], v[120:123], v[2:17]
	ds_read_b128 v[108:111], v226
	ds_read_b128 v[116:119], v230
	ds_read_b128 v[120:123], v230 offset:4096
	ds_read_b128 v[112:115], v226 offset:4096
	s_waitcnt lgkmcnt(5)
	v_mfma_f32_32x32x16_bf16 v[50:65], v[126:129], v[134:137], v[50:65]
	v_mfma_f32_32x32x16_bf16 v[18:33], v[126:129], v[138:141], v[18:33]
	s_waitcnt lgkmcnt(4)
	v_mfma_f32_32x32x16_bf16 v[34:49], v[130:133], v[134:137], v[34:49]
	v_mfma_f32_32x32x16_bf16 v[2:17], v[130:133], v[138:141], v[2:17]
	ds_read_b128 v[126:129], v227
	ds_read_b128 v[134:137], v231
	ds_read_b128 v[138:141], v231 offset:4096
	ds_read_b128 v[130:133], v227 offset:4096
	s_waitcnt lgkmcnt(5)
	v_mfma_f32_32x32x16_bf16 v[50:65], v[108:111], v[116:119], v[50:65]
	v_mfma_f32_32x32x16_bf16 v[18:33], v[108:111], v[120:123], v[18:33]
	s_waitcnt lgkmcnt(4)
	v_mfma_f32_32x32x16_bf16 v[34:49], v[112:115], v[116:119], v[34:49]
	v_mfma_f32_32x32x16_bf16 v[2:17], v[112:115], v[120:123], v[2:17]
	s_waitcnt lgkmcnt(0)
	s_waitcnt vmcnt(0)
	s_barrier
	ds_read_b128 v[108:111], v216
	ds_read_b128 v[116:119], v220
	ds_read_b128 v[120:123], v220 offset:4096
	ds_read_b128 v[112:115], v216 offset:4096
	v_mfma_f32_32x32x16_bf16 v[50:65], v[126:129], v[134:137], v[50:65]
	v_mfma_f32_32x32x16_bf16 v[18:33], v[126:129], v[138:141], v[18:33]
	v_mfma_f32_32x32x16_bf16 v[34:49], v[130:133], v[134:137], v[34:49]
	v_mfma_f32_32x32x16_bf16 v[2:17], v[130:133], v[138:141], v[2:17]
	ds_read_b128 v[126:129], v217
	ds_read_b128 v[134:137], v221
	ds_read_b128 v[138:141], v221 offset:4096
	ds_read_b128 v[130:133], v217 offset:4096
	s_waitcnt lgkmcnt(5)
	v_mfma_f32_32x32x16_bf16 v[50:65], v[108:111], v[116:119], v[50:65]
	v_mfma_f32_32x32x16_bf16 v[18:33], v[108:111], v[120:123], v[18:33]
	s_waitcnt lgkmcnt(4)
	v_mfma_f32_32x32x16_bf16 v[34:49], v[112:115], v[116:119], v[34:49]
	v_mfma_f32_32x32x16_bf16 v[2:17], v[112:115], v[120:123], v[2:17]
	ds_read_b128 v[108:111], v218
	ds_read_b128 v[116:119], v222
	ds_read_b128 v[120:123], v222 offset:4096
	ds_read_b128 v[112:115], v218 offset:4096
	s_waitcnt lgkmcnt(5)
	v_mfma_f32_32x32x16_bf16 v[50:65], v[126:129], v[134:137], v[50:65]
	v_mfma_f32_32x32x16_bf16 v[18:33], v[126:129], v[138:141], v[18:33]
	s_waitcnt lgkmcnt(4)
	v_mfma_f32_32x32x16_bf16 v[34:49], v[130:133], v[134:137], v[34:49]
	v_mfma_f32_32x32x16_bf16 v[2:17], v[130:133], v[138:141], v[2:17]
	ds_read_b128 v[126:129], v219
	ds_read_b128 v[134:137], v223
	ds_read_b128 v[138:141], v223 offset:4096
	ds_read_b128 v[130:133], v219 offset:4096
	s_waitcnt lgkmcnt(5)
	v_mfma_f32_32x32x16_bf16 v[50:65], v[108:111], v[116:119], v[50:65]
	v_mfma_f32_32x32x16_bf16 v[18:33], v[108:111], v[120:123], v[18:33]
	s_waitcnt lgkmcnt(4)
	v_mfma_f32_32x32x16_bf16 v[34:49], v[112:115], v[116:119], v[34:49]
	v_mfma_f32_32x32x16_bf16 v[2:17], v[112:115], v[120:123], v[2:17]
	s_waitcnt lgkmcnt(0)
	s_waitcnt vmcnt(0)
	s_barrier
.Lg1_done:
	v_mfma_f32_32x32x16_bf16 v[50:65], v[126:129], v[134:137], v[50:65]
	v_mfma_f32_32x32x16_bf16 v[18:33], v[126:129], v[138:141], v[18:33]
	v_mfma_f32_32x32x16_bf16 v[34:49], v[130:133], v[134:137], v[34:49]
	v_mfma_f32_32x32x16_bf16 v[2:17], v[130:133], v[138:141], v[2:17]
	s_ashr_i32 s11, s38, 2
	s_waitcnt vmcnt(0)
	s_cmp_lt_u32 s38, 4
	s_cselect_b64 s[40:41], -1, 0
	s_mov_b64 s[8:9], -1
	s_and_b64 vcc, exec, s[40:41]
	s_mov_b64 s[36:37], -1
	s_cbranch_vccnz .LBB0_219
	s_cmp_gt_u32 s11, 5
	s_mov_b64 s[36:37], 0
	s_cbranch_scc1 .LBB0_219
	s_lshr_b32 s0, s38, 2
	s_lshr_b32 s0, 50, s0
	s_bitcmp1_b32 s0, 0
	s_cselect_b64 s[36:37], -1, 0

.Lg2_loop:
	ds_read_b128 v[102:105], v225
	ds_read_b128 v[110:113], v229
	ds_read_b128 v[114:117], v229 offset:4096
	ds_read_b128 v[106:109], v225 offset:4096
	s_add_i32 m0, s19, 0x1bf80
	s_waitcnt lgkmcnt(5)
	v_mfma_f32_32x32x16_bf16 v[48:63], v[84:87], v[92:95], 0
	global_load_lds_dwordx4 v124, s[12:13] offset:-1664
	s_add_i32 m0, s19, 0x1df80
	v_mfma_f32_32x32x16_bf16 v[32:47], v[84:87], v[96:99], 0
	global_load_lds_dwordx4 v125, s[12:13] offset:-1664
	s_waitcnt lgkmcnt(4)
	v_mfma_f32_32x32x16_bf16 v[16:31], v[88:91], v[92:95], 0
	v_mfma_f32_32x32x16_bf16 v[0:15], v[88:91], v[96:99], 0
	ds_read_b128 v[84:87], v226
	ds_read_b128 v[92:95], v230
	ds_read_b128 v[96:99], v230 offset:4096
	ds_read_b128 v[88:91], v226 offset:4096
	s_add_i32 m0, s19, 0x1ff80
	s_waitcnt lgkmcnt(5)
	v_mfma_f32_32x32x16_bf16 v[48:63], v[102:105], v[110:113], v[48:63]
	global_load_lds_dwordx4 v124, s[14:15] offset:-1664
	s_add_i32 m0, s19, 0x21f80
	v_mfma_f32_32x32x16_bf16 v[32:47], v[102:105], v[114:117], v[32:47]
	global_load_lds_dwordx4 v125, s[14:15] offset:-1664
	s_waitcnt lgkmcnt(4)
	v_mfma_f32_32x32x16_bf16 v[16:31], v[106:109], v[110:113], v[16:31]
	v_mfma_f32_32x32x16_bf16 v[0:15], v[106:109], v[114:117], v[0:15]
	ds_read_b128 v[102:105], v227
	ds_read_b128 v[110:113], v231
	ds_read_b128 v[114:117], v231 offset:4096
	ds_read_b128 v[106:109], v227 offset:4096
	s_add_i32 m0, s19, 0x23f80
	s_waitcnt lgkmcnt(5)
	v_mfma_f32_32x32x16_bf16 v[48:63], v[84:87], v[92:95], v[48:63]
	global_load_lds_dwordx4 v126, s[14:15] offset:-1664
	s_add_i32 m0, s19, 0x25f80
	v_mfma_f32_32x32x16_bf16 v[32:47], v[84:87], v[96:99], v[32:47]
	global_load_lds_dwordx4 v127, s[14:15] offset:-1664
	s_waitcnt lgkmcnt(4)
	v_mfma_f32_32x32x16_bf16 v[16:31], v[88:91], v[92:95], v[16:31]
	v_mfma_f32_32x32x16_bf16 v[0:15], v[88:91], v[96:99], v[0:15]
	s_waitcnt lgkmcnt(0)
	s_waitcnt vmcnt(23)
	s_barrier
	ds_read_b128 v[84:87], v224 offset:49152
	ds_read_b128 v[92:95], v228 offset:49152
	ds_read_b128 v[96:99], v228 offset:53248
	ds_read_b128 v[88:91], v224 offset:53248
	v_mfma_f32_32x32x16_bf16 v[48:63], v[102:105], v[110:113], v[48:63]
	v_mfma_f32_32x32x16_bf16 v[32:47], v[102:105], v[114:117], v[32:47]
	v_mfma_f32_32x32x16_bf16 v[16:31], v[106:109], v[110:113], v[16:31]
	v_mfma_f32_32x32x16_bf16 v[0:15], v[106:109], v[114:117], v[0:15]
	ds_read_b128 v[102:105], v225 offset:49152
	ds_read_b128 v[110:113], v229 offset:49152
	ds_read_b128 v[114:117], v229 offset:53248
	ds_read_b128 v[106:109], v225 offset:53248
	s_add_i32 m0, s19, 0x700
	s_waitcnt lgkmcnt(5)
	v_mfma_f32_32x32x16_bf16 v[48:63], v[84:87], v[92:95], v[48:63]
	global_load_lds_dwordx4 v124, s[12:13] offset:-1536
	s_add_i32 m0, s19, 0x2700
	v_mfma_f32_32x32x16_bf16 v[32:47], v[84:87], v[96:99], v[32:47]
	global_load_lds_dwordx4 v125, s[12:13] offset:-1536
	s_waitcnt lgkmcnt(4)
	v_mfma_f32_32x32x16_bf16 v[16:31], v[88:91], v[92:95], v[16:31]
	v_mfma_f32_32x32x16_bf16 v[0:15], v[88:91], v[96:99], v[0:15]
	ds_read_b128 v[84:87], v226 offset:49152
	ds_read_b128 v[92:95], v230 offset:49152
	ds_read_b128 v[96:99], v230 offset:53248
	ds_read_b128 v[88:91], v226 offset:53248
	s_add_i32 m0, s19, 0x4700
	s_waitcnt lgkmcnt(5)
	v_mfma_f32_32x32x16_bf16 v[48:63], v[102:105], v[110:113], v[48:63]
	global_load_lds_dwordx4 v124, s[14:15] offset:-1536
	s_add_i32 m0, s19, 0x6700
	v_mfma_f32_32x32x16_bf16 v[32:47], v[102:105], v[114:117], v[32:47]
	global_load_lds_dwordx4 v125, s[14:15] offset:-1536
	s_waitcnt lgkmcnt(4)
	v_mfma_f32_32x32x16_bf16 v[16:31], v[106:109], v[110:113], v[16:31]
	v_mfma_f32_32x32x16_bf16 v[0:15], v[106:109], v[114:117], v[0:15]
	ds_read_b128 v[102:105], v227 offset:49152
	ds_read_b128 v[110:113], v231 offset:49152
	ds_read_b128 v[114:117], v231 offset:53248
	ds_read_b128 v[106:109], v227 offset:53248
	s_add_i32 m0, s19, 0x8700
	s_waitcnt lgkmcnt(5)
	v_mfma_f32_32x32x16_bf16 v[48:63], v[84:87], v[92:95], v[48:63]
	global_load_lds_dwordx4 v126, s[14:15] offset:-1536
	s_add_i32 m0, s19, 0xa700
	v_mfma_f32_32x32x16_bf16 v[32:47], v[84:87], v[96:99], v[32:47]
	global_load_lds_dwordx4 v127, s[14:15] offset:-1536
	s_waitcnt lgkmcnt(4)
	v_mfma_f32_32x32x16_bf16 v[16:31], v[88:91], v[92:95], v[16:31]
	v_mfma_f32_32x32x16_bf16 v[0:15], v[88:91], v[96:99], v[0:15]
	s_waitcnt lgkmcnt(0)
	s_waitcnt vmcnt(6)
	s_barrier
	ds_read_b128 v[84:87], v232
	ds_read_b128 v[92:95], v236
	ds_read_b128 v[96:99], v236 offset:4096
	ds_read_b128 v[88:91], v232 offset:4096
	v_mfma_f32_32x32x16_bf16 v[48:63], v[102:105], v[110:113], v[48:63]
	v_mfma_f32_32x32x16_bf16 v[32:47], v[102:105], v[114:117], v[32:47]
	v_mfma_f32_32x32x16_bf16 v[16:31], v[106:109], v[110:113], v[16:31]
	v_mfma_f32_32x32x16_bf16 v[0:15], v[106:109], v[114:117], v[0:15]
	ds_read_b128 v[102:105], v233
	ds_read_b128 v[110:113], v237
	ds_read_b128 v[114:117], v237 offset:4096
	ds_read_b128 v[106:109], v233 offset:4096
	s_add_i32 m0, s19, 0xc680
	s_waitcnt lgkmcnt(5)
	v_mfma_f32_32x32x16_bf16 v[48:63], v[84:87], v[92:95], v[48:63]
	global_load_lds_dwordx4 v124, s[12:13] offset:-1408
	s_add_i32 m0, s19, 0xe680
	v_mfma_f32_32x32x16_bf16 v[32:47], v[84:87], v[96:99], v[32:47]
	global_load_lds_dwordx4 v125, s[12:13] offset:-1408
	s_waitcnt lgkmcnt(4)
	v_mfma_f32_32x32x16_bf16 v[16:31], v[88:91], v[92:95], v[16:31]
	v_mfma_f32_32x32x16_bf16 v[0:15], v[88:91], v[96:99], v[0:15]
	ds_read_b128 v[84:87], v234
	ds_read_b128 v[92:95], v238
	ds_read_b128 v[96:99], v238 offset:4096
	ds_read_b128 v[88:91], v234 offset:4096
	s_add_i32 m0, s19, 0x10680
	s_waitcnt lgkmcnt(5)
	v_mfma_f32_32x32x16_bf16 v[48:63], v[102:105], v[110:113], v[48:63]
	global_load_lds_dwordx4 v124, s[14:15] offset:-1408
	s_add_i32 m0, s19, 0x12680
	v_mfma_f32_32x32x16_bf16 v[32:47], v[102:105], v[114:117], v[32:47]
	global_load_lds_dwordx4 v125, s[14:15] offset:-1408
	s_waitcnt lgkmcnt(4)
	v_mfma_f32_32x32x16_bf16 v[16:31], v[106:109], v[110:113], v[16:31]
	v_mfma_f32_32x32x16_bf16 v[0:15], v[106:109], v[114:117], v[0:15]
	ds_read_b128 v[102:105], v235
	ds_read_b128 v[110:113], v239
	ds_read_b128 v[114:117], v239 offset:4096
	ds_read_b128 v[106:109], v235 offset:4096
	s_add_i32 m0, s19, 0x14680
	s_waitcnt lgkmcnt(5)
	v_mfma_f32_32x32x16_bf16 v[48:63], v[84:87], v[92:95], v[48:63]
	global_load_lds_dwordx4 v126, s[14:15] offset:-1408
	s_add_i32 m0, s19, 0x16680
	v_mfma_f32_32x32x16_bf16 v[32:47], v[84:87], v[96:99], v[32:47]
	global_load_lds_dwordx4 v127, s[14:15] offset:-1408
	s_waitcnt lgkmcnt(4)
	v_mfma_f32_32x32x16_bf16 v[16:31], v[88:91], v[92:95], v[16:31]
	v_mfma_f32_32x32x16_bf16 v[0:15], v[88:91], v[96:99], v[0:15]
	s_waitcnt lgkmcnt(0)
	s_waitcnt vmcnt(6)
	s_barrier
	ds_read_b128 v[84:87], v224
	ds_read_b128 v[92:95], v228
	ds_read_b128 v[96:99], v228 offset:4096
	ds_read_b128 v[88:91], v224 offset:4096
	v_mfma_f32_32x32x16_bf16 v[48:63], v[102:105], v[110:113], v[48:63]
	v_mfma_f32_32x32x16_bf16 v[32:47], v[102:105], v[114:117], v[32:47]
	v_mfma_f32_32x32x16_bf16 v[16:31], v[106:109], v[110:113], v[16:31]
	v_mfma_f32_32x32x16_bf16 v[0:15], v[106:109], v[114:117], v[0:15]
	ds_read_b128 v[102:105], v225
	ds_read_b128 v[110:113], v229
	ds_read_b128 v[114:117], v229 offset:4096
	ds_read_b128 v[106:109], v225 offset:4096
	s_add_i32 m0, s19, 0x1be00
	s_waitcnt lgkmcnt(5)
	v_mfma_f32_32x32x16_bf16 v[48:63], v[84:87], v[92:95], v[48:63]
	global_load_lds_dwordx4 v124, s[12:13] offset:-1280
	s_add_i32 m0, s19, 0x1de00
	v_mfma_f32_32x32x16_bf16 v[32:47], v[84:87], v[96:99], v[32:47]
	global_load_lds_dwordx4 v125, s[12:13] offset:-1280
	s_waitcnt lgkmcnt(4)
	v_mfma_f32_32x32x16_bf16 v[16:31], v[88:91], v[92:95], v[16:31]
	v_mfma_f32_32x32x16_bf16 v[0:15], v[88:91], v[96:99], v[0:15]
	ds_read_b128 v[84:87], v226
	ds_read_b128 v[92:95], v230
	ds_read_b128 v[96:99], v230 offset:4096
	ds_read_b128 v[88:91], v226 offset:4096
	s_add_i32 m0, s19, 0x1fe00
	s_waitcnt lgkmcnt(5)
	v_mfma_f32_32x32x16_bf16 v[48:63], v[102:105], v[110:113], v[48:63]
	global_load_lds_dwordx4 v124, s[14:15] offset:-1280
	s_add_i32 m0, s19, 0x21e00
	v_mfma_f32_32x32x16_bf16 v[32:47], v[102:105], v[114:117], v[32:47]
	global_load_lds_dwordx4 v125, s[14:15] offset:-1280
	s_waitcnt lgkmcnt(4)
	v_mfma_f32_32x32x16_bf16 v[16:31], v[106:109], v[110:113], v[16:31]
	v_mfma_f32_32x32x16_bf16 v[0:15], v[106:109], v[114:117], v[0:15]
	ds_read_b128 v[102:105], v227
	ds_read_b128 v[110:113], v231
	ds_read_b128 v[114:117], v231 offset:4096
	ds_read_b128 v[106:109], v227 offset:4096
	s_add_i32 m0, s19, 0x23e00
	s_waitcnt lgkmcnt(5)
	v_mfma_f32_32x32x16_bf16 v[48:63], v[84:87], v[92:95], v[48:63]
	global_load_lds_dwordx4 v126, s[14:15] offset:-1280
	s_add_i32 m0, s19, 0x25e00
	v_mfma_f32_32x32x16_bf16 v[32:47], v[84:87], v[96:99], v[32:47]
	global_load_lds_dwordx4 v127, s[14:15] offset:-1280
	s_waitcnt lgkmcnt(4)
	v_mfma_f32_32x32x16_bf16 v[16:31], v[88:91], v[92:95], v[16:31]
	v_mfma_f32_32x32x16_bf16 v[0:15], v[88:91], v[96:99], v[0:15]
	s_waitcnt lgkmcnt(0)
	s_waitcnt vmcnt(6)
	s_barrier
	ds_read_b128 v[84:87], v224 offset:49152
	ds_read_b128 v[92:95], v228 offset:49152
	ds_read_b128 v[96:99], v228 offset:53248
	ds_read_b128 v[88:91], v224 offset:53248
	v_mfma_f32_32x32x16_bf16 v[48:63], v[102:105], v[110:113], v[48:63]
	v_mfma_f32_32x32x16_bf16 v[32:47], v[102:105], v[114:117], v[32:47]
	v_mfma_f32_32x32x16_bf16 v[16:31], v[106:109], v[110:113], v[16:31]
	v_mfma_f32_32x32x16_bf16 v[0:15], v[106:109], v[114:117], v[0:15]
	ds_read_b128 v[102:105], v225 offset:49152
	ds_read_b128 v[110:113], v229 offset:49152
	ds_read_b128 v[114:117], v229 offset:53248
	ds_read_b128 v[106:109], v225 offset:53248
	s_add_i32 m0, s19, 0x580
	s_waitcnt lgkmcnt(5)
	v_mfma_f32_32x32x16_bf16 v[48:63], v[84:87], v[92:95], v[48:63]
	global_load_lds_dwordx4 v124, s[12:13] offset:-1152
	s_add_i32 m0, s19, 0x2580
	v_mfma_f32_32x32x16_bf16 v[32:47], v[84:87], v[96:99], v[32:47]
	global_load_lds_dwordx4 v125, s[12:13] offset:-1152
	s_waitcnt lgkmcnt(4)
	v_mfma_f32_32x32x16_bf16 v[16:31], v[88:91], v[92:95], v[16:31]
	v_mfma_f32_32x32x16_bf16 v[0:15], v[88:91], v[96:99], v[0:15]
	ds_read_b128 v[84:87], v226 offset:49152
	ds_read_b128 v[92:95], v230 offset:49152
	ds_read_b128 v[96:99], v230 offset:53248
	ds_read_b128 v[88:91], v226 offset:53248
	s_add_i32 m0, s19, 0x4580
	s_waitcnt lgkmcnt(5)
	v_mfma_f32_32x32x16_bf16 v[48:63], v[102:105], v[110:113], v[48:63]
	global_load_lds_dwordx4 v124, s[14:15] offset:-1152
	s_add_i32 m0, s19, 0x6580
	v_mfma_f32_32x32x16_bf16 v[32:47], v[102:105], v[114:117], v[32:47]
	global_load_lds_dwordx4 v125, s[14:15] offset:-1152
	s_waitcnt lgkmcnt(4)
	v_mfma_f32_32x32x16_bf16 v[16:31], v[106:109], v[110:113], v[16:31]
	v_mfma_f32_32x32x16_bf16 v[0:15], v[106:109], v[114:117], v[0:15]
	ds_read_b128 v[102:105], v227 offset:49152
	ds_read_b128 v[110:113], v231 offset:49152
	ds_read_b128 v[114:117], v231 offset:53248
	ds_read_b128 v[106:109], v227 offset:53248
	s_add_i32 m0, s19, 0x8580
	s_waitcnt lgkmcnt(5)
	v_mfma_f32_32x32x16_bf16 v[48:63], v[84:87], v[92:95], v[48:63]
	global_load_lds_dwordx4 v126, s[14:15] offset:-1152
	s_add_i32 m0, s19, 0xa580
	v_mfma_f32_32x32x16_bf16 v[32:47], v[84:87], v[96:99], v[32:47]
	global_load_lds_dwordx4 v127, s[14:15] offset:-1152
	s_waitcnt lgkmcnt(4)
	v_mfma_f32_32x32x16_bf16 v[16:31], v[88:91], v[92:95], v[16:31]
	v_mfma_f32_32x32x16_bf16 v[0:15], v[88:91], v[96:99], v[0:15]
	s_waitcnt lgkmcnt(0)
	s_waitcnt vmcnt(6)
	s_barrier
	ds_read_b128 v[84:87], v232
	ds_read_b128 v[92:95], v236
	ds_read_b128 v[96:99], v236 offset:4096
	ds_read_b128 v[88:91], v232 offset:4096
	v_mfma_f32_32x32x16_bf16 v[48:63], v[102:105], v[110:113], v[48:63]
	v_mfma_f32_32x32x16_bf16 v[32:47], v[102:105], v[114:117], v[32:47]
	v_mfma_f32_32x32x16_bf16 v[16:31], v[106:109], v[110:113], v[16:31]
	v_mfma_f32_32x32x16_bf16 v[0:15], v[106:109], v[114:117], v[0:15]
	ds_read_b128 v[102:105], v233
	ds_read_b128 v[110:113], v237
	ds_read_b128 v[114:117], v237 offset:4096
	ds_read_b128 v[106:109], v233 offset:4096
	s_add_i32 m0, s19, 0xc500
	s_waitcnt lgkmcnt(5)
	v_mfma_f32_32x32x16_bf16 v[48:63], v[84:87], v[92:95], v[48:63]
	global_load_lds_dwordx4 v124, s[12:13] offset:-1024
	s_add_i32 m0, s19, 0xe500
	v_mfma_f32_32x32x16_bf16 v[32:47], v[84:87], v[96:99], v[32:47]
	global_load_lds_dwordx4 v125, s[12:13] offset:-1024
	s_waitcnt lgkmcnt(4)
	v_mfma_f32_32x32x16_bf16 v[16:31], v[88:91], v[92:95], v[16:31]
	v_mfma_f32_32x32x16_bf16 v[0:15], v[88:91], v[96:99], v[0:15]
	ds_read_b128 v[84:87], v234
	ds_read_b128 v[92:95], v238
	ds_read_b128 v[96:99], v238 offset:4096
	ds_read_b128 v[88:91], v234 offset:4096
	s_add_i32 m0, s19, 0x10500
	s_waitcnt lgkmcnt(5)
	v_mfma_f32_32x32x16_bf16 v[48:63], v[102:105], v[110:113], v[48:63]
	global_load_lds_dwordx4 v124, s[14:15] offset:-1024
	s_add_i32 m0, s19, 0x12500
	v_mfma_f32_32x32x16_bf16 v[32:47], v[102:105], v[114:117], v[32:47]
	global_load_lds_dwordx4 v125, s[14:15] offset:-1024
	s_waitcnt lgkmcnt(4)
	v_mfma_f32_32x32x16_bf16 v[16:31], v[106:109], v[110:113], v[16:31]
	v_mfma_f32_32x32x16_bf16 v[0:15], v[106:109], v[114:117], v[0:15]
	ds_read_b128 v[102:105], v235
	ds_read_b128 v[110:113], v239
	ds_read_b128 v[114:117], v239 offset:4096
	ds_read_b128 v[106:109], v235 offset:4096
	s_add_i32 m0, s19, 0x14500
	s_waitcnt lgkmcnt(5)
	v_mfma_f32_32x32x16_bf16 v[48:63], v[84:87], v[92:95], v[48:63]
	global_load_lds_dwordx4 v126, s[14:15] offset:-1024
	s_add_i32 m0, s19, 0x16500
	v_mfma_f32_32x32x16_bf16 v[32:47], v[84:87], v[96:99], v[32:47]
	global_load_lds_dwordx4 v127, s[14:15] offset:-1024
	s_waitcnt lgkmcnt(4)
	v_mfma_f32_32x32x16_bf16 v[16:31], v[88:91], v[92:95], v[16:31]
	v_mfma_f32_32x32x16_bf16 v[0:15], v[88:91], v[96:99], v[0:15]
	s_waitcnt lgkmcnt(0)
	s_waitcnt vmcnt(6)
	s_barrier
	ds_read_b128 v[84:87], v224
	ds_read_b128 v[92:95], v228
	ds_read_b128 v[96:99], v228 offset:4096
	ds_read_b128 v[88:91], v224 offset:4096
	v_mfma_f32_32x32x16_bf16 v[48:63], v[102:105], v[110:113], v[48:63]
	v_mfma_f32_32x32x16_bf16 v[32:47], v[102:105], v[114:117], v[32:47]
	v_mfma_f32_32x32x16_bf16 v[16:31], v[106:109], v[110:113], v[16:31]
	v_mfma_f32_32x32x16_bf16 v[0:15], v[106:109], v[114:117], v[0:15]
	ds_read_b128 v[102:105], v225
	ds_read_b128 v[110:113], v229
	ds_read_b128 v[114:117], v229 offset:4096
	ds_read_b128 v[106:109], v225 offset:4096
	s_add_i32 m0, s19, 0x1bc80
	s_waitcnt lgkmcnt(5)
	v_mfma_f32_32x32x16_bf16 v[48:63], v[84:87], v[92:95], v[48:63]
	global_load_lds_dwordx4 v124, s[12:13] offset:-896
	s_add_i32 m0, s19, 0x1dc80
	v_mfma_f32_32x32x16_bf16 v[32:47], v[84:87], v[96:99], v[32:47]
	global_load_lds_dwordx4 v125, s[12:13] offset:-896
	s_waitcnt lgkmcnt(4)
	v_mfma_f32_32x32x16_bf16 v[16:31], v[88:91], v[92:95], v[16:31]
	v_mfma_f32_32x32x16_bf16 v[0:15], v[88:91], v[96:99], v[0:15]
	ds_read_b128 v[84:87], v226
	ds_read_b128 v[92:95], v230
	ds_read_b128 v[96:99], v230 offset:4096
	ds_read_b128 v[88:91], v226 offset:4096
	s_add_i32 m0, s19, 0x1fc80
	s_waitcnt lgkmcnt(5)
	v_mfma_f32_32x32x16_bf16 v[48:63], v[102:105], v[110:113], v[48:63]
	global_load_lds_dwordx4 v124, s[14:15] offset:-896
	s_add_i32 m0, s19, 0x21c80
	v_mfma_f32_32x32x16_bf16 v[32:47], v[102:105], v[114:117], v[32:47]
	global_load_lds_dwordx4 v125, s[14:15] offset:-896
	s_waitcnt lgkmcnt(4)
	v_mfma_f32_32x32x16_bf16 v[16:31], v[106:109], v[110:113], v[16:31]
	v_mfma_f32_32x32x16_bf16 v[0:15], v[106:109], v[114:117], v[0:15]
	ds_read_b128 v[102:105], v227
	ds_read_b128 v[110:113], v231
	ds_read_b128 v[114:117], v231 offset:4096
	ds_read_b128 v[106:109], v227 offset:4096
	s_add_i32 m0, s19, 0x23c80
	s_waitcnt lgkmcnt(5)
	v_mfma_f32_32x32x16_bf16 v[48:63], v[84:87], v[92:95], v[48:63]
	global_load_lds_dwordx4 v126, s[14:15] offset:-896
	s_add_i32 m0, s19, 0x25c80
	v_mfma_f32_32x32x16_bf16 v[32:47], v[84:87], v[96:99], v[32:47]
	global_load_lds_dwordx4 v127, s[14:15] offset:-896
	s_waitcnt lgkmcnt(4)
	v_mfma_f32_32x32x16_bf16 v[16:31], v[88:91], v[92:95], v[16:31]
	v_mfma_f32_32x32x16_bf16 v[0:15], v[88:91], v[96:99], v[0:15]
	s_waitcnt lgkmcnt(0)
	s_waitcnt vmcnt(6)
	s_barrier
	ds_read_b128 v[84:87], v224 offset:49152
	ds_read_b128 v[92:95], v228 offset:49152
	ds_read_b128 v[96:99], v228 offset:53248
	ds_read_b128 v[88:91], v224 offset:53248
	v_mfma_f32_32x32x16_bf16 v[48:63], v[102:105], v[110:113], v[48:63]
	v_mfma_f32_32x32x16_bf16 v[32:47], v[102:105], v[114:117], v[32:47]
	v_mfma_f32_32x32x16_bf16 v[16:31], v[106:109], v[110:113], v[16:31]
	v_mfma_f32_32x32x16_bf16 v[0:15], v[106:109], v[114:117], v[0:15]
	ds_read_b128 v[102:105], v225 offset:49152
	ds_read_b128 v[110:113], v229 offset:49152
	ds_read_b128 v[114:117], v229 offset:53248
	ds_read_b128 v[106:109], v225 offset:53248
	s_add_i32 m0, s19, 0x400
	s_waitcnt lgkmcnt(5)
	v_mfma_f32_32x32x16_bf16 v[48:63], v[84:87], v[92:95], v[48:63]
	global_load_lds_dwordx4 v124, s[12:13] offset:-768
	s_add_i32 m0, s19, 0x2400
	v_mfma_f32_32x32x16_bf16 v[32:47], v[84:87], v[96:99], v[32:47]
	global_load_lds_dwordx4 v125, s[12:13] offset:-768
	s_waitcnt lgkmcnt(4)
	v_mfma_f32_32x32x16_bf16 v[16:31], v[88:91], v[92:95], v[16:31]
	v_mfma_f32_32x32x16_bf16 v[0:15], v[88:91], v[96:99], v[0:15]
	ds_read_b128 v[84:87], v226 offset:49152
	ds_read_b128 v[92:95], v230 offset:49152
	ds_read_b128 v[96:99], v230 offset:53248
	ds_read_b128 v[88:91], v226 offset:53248
	s_add_i32 m0, s19, 0x4400
	s_waitcnt lgkmcnt(5)
	v_mfma_f32_32x32x16_bf16 v[48:63], v[102:105], v[110:113], v[48:63]
	global_load_lds_dwordx4 v124, s[14:15] offset:-768
	s_add_i32 m0, s19, 0x6400
	v_mfma_f32_32x32x16_bf16 v[32:47], v[102:105], v[114:117], v[32:47]
	global_load_lds_dwordx4 v125, s[14:15] offset:-768
	s_waitcnt lgkmcnt(4)
	v_mfma_f32_32x32x16_bf16 v[16:31], v[106:109], v[110:113], v[16:31]
	v_mfma_f32_32x32x16_bf16 v[0:15], v[106:109], v[114:117], v[0:15]
	ds_read_b128 v[102:105], v227 offset:49152
	ds_read_b128 v[110:113], v231 offset:49152
	ds_read_b128 v[114:117], v231 offset:53248
	ds_read_b128 v[106:109], v227 offset:53248
	s_add_i32 m0, s19, 0x8400
	s_waitcnt lgkmcnt(5)
	v_mfma_f32_32x32x16_bf16 v[48:63], v[84:87], v[92:95], v[48:63]
	global_load_lds_dwordx4 v126, s[14:15] offset:-768
	s_add_i32 m0, s19, 0xa400
	v_mfma_f32_32x32x16_bf16 v[32:47], v[84:87], v[96:99], v[32:47]
	global_load_lds_dwordx4 v127, s[14:15] offset:-768
	s_waitcnt lgkmcnt(4)
	v_mfma_f32_32x32x16_bf16 v[16:31], v[88:91], v[92:95], v[16:31]
	v_mfma_f32_32x32x16_bf16 v[0:15], v[88:91], v[96:99], v[0:15]
	s_waitcnt lgkmcnt(0)
	s_waitcnt vmcnt(6)
	s_barrier
	ds_read_b128 v[84:87], v232
	ds_read_b128 v[92:95], v236
	ds_read_b128 v[96:99], v236 offset:4096
	ds_read_b128 v[88:91], v232 offset:4096
	v_mfma_f32_32x32x16_bf16 v[48:63], v[102:105], v[110:113], v[48:63]
	v_mfma_f32_32x32x16_bf16 v[32:47], v[102:105], v[114:117], v[32:47]
	v_mfma_f32_32x32x16_bf16 v[16:31], v[106:109], v[110:113], v[16:31]
	v_mfma_f32_32x32x16_bf16 v[0:15], v[106:109], v[114:117], v[0:15]
	ds_read_b128 v[102:105], v233
	ds_read_b128 v[110:113], v237
	ds_read_b128 v[114:117], v237 offset:4096
	ds_read_b128 v[106:109], v233 offset:4096
	s_add_i32 m0, s19, 0xc380
	s_waitcnt lgkmcnt(5)
	v_mfma_f32_32x32x16_bf16 v[48:63], v[84:87], v[92:95], v[48:63]
	global_load_lds_dwordx4 v124, s[12:13] offset:-640
	s_add_i32 m0, s19, 0xe380
	v_mfma_f32_32x32x16_bf16 v[32:47], v[84:87], v[96:99], v[32:47]
	global_load_lds_dwordx4 v125, s[12:13] offset:-640
	s_waitcnt lgkmcnt(4)
	v_mfma_f32_32x32x16_bf16 v[16:31], v[88:91], v[92:95], v[16:31]
	v_mfma_f32_32x32x16_bf16 v[0:15], v[88:91], v[96:99], v[0:15]
	ds_read_b128 v[84:87], v234
	ds_read_b128 v[92:95], v238
	ds_read_b128 v[96:99], v238 offset:4096
	ds_read_b128 v[88:91], v234 offset:4096
	s_add_i32 m0, s19, 0x10380
	s_waitcnt lgkmcnt(5)
	v_mfma_f32_32x32x16_bf16 v[48:63], v[102:105], v[110:113], v[48:63]
	global_load_lds_dwordx4 v124, s[14:15] offset:-640
	s_add_i32 m0, s19, 0x12380
	v_mfma_f32_32x32x16_bf16 v[32:47], v[102:105], v[114:117], v[32:47]
	global_load_lds_dwordx4 v125, s[14:15] offset:-640
	s_waitcnt lgkmcnt(4)
	v_mfma_f32_32x32x16_bf16 v[16:31], v[106:109], v[110:113], v[16:31]
	v_mfma_f32_32x32x16_bf16 v[0:15], v[106:109], v[114:117], v[0:15]
	ds_read_b128 v[102:105], v235
	ds_read_b128 v[110:113], v239
	ds_read_b128 v[114:117], v239 offset:4096
	ds_read_b128 v[106:109], v235 offset:4096
	s_add_i32 m0, s19, 0x14380
	s_waitcnt lgkmcnt(5)
	v_mfma_f32_32x32x16_bf16 v[48:63], v[84:87], v[92:95], v[48:63]
	global_load_lds_dwordx4 v126, s[14:15] offset:-640
	s_add_i32 m0, s19, 0x16380
	v_mfma_f32_32x32x16_bf16 v[32:47], v[84:87], v[96:99], v[32:47]
	global_load_lds_dwordx4 v127, s[14:15] offset:-640
	s_waitcnt lgkmcnt(4)
	v_mfma_f32_32x32x16_bf16 v[16:31], v[88:91], v[92:95], v[16:31]
	v_mfma_f32_32x32x16_bf16 v[0:15], v[88:91], v[96:99], v[0:15]
	s_waitcnt lgkmcnt(0)
	s_waitcnt vmcnt(6)
	s_barrier
	ds_read_b128 v[84:87], v224
	ds_read_b128 v[92:95], v228
	ds_read_b128 v[96:99], v228 offset:4096
	ds_read_b128 v[88:91], v224 offset:4096
	v_mfma_f32_32x32x16_bf16 v[48:63], v[102:105], v[110:113], v[48:63]
	v_mfma_f32_32x32x16_bf16 v[32:47], v[102:105], v[114:117], v[32:47]
	v_mfma_f32_32x32x16_bf16 v[16:31], v[106:109], v[110:113], v[16:31]
	v_mfma_f32_32x32x16_bf16 v[0:15], v[106:109], v[114:117], v[0:15]
	ds_read_b128 v[102:105], v225
	ds_read_b128 v[110:113], v229
	ds_read_b128 v[114:117], v229 offset:4096
	ds_read_b128 v[106:109], v225 offset:4096
	s_add_i32 m0, s19, 0x1bb00
	s_waitcnt lgkmcnt(5)
	v_mfma_f32_32x32x16_bf16 v[48:63], v[84:87], v[92:95], v[48:63]
	global_load_lds_dwordx4 v124, s[12:13] offset:-512
	s_add_i32 m0, s19, 0x1db00
	v_mfma_f32_32x32x16_bf16 v[32:47], v[84:87], v[96:99], v[32:47]
	global_load_lds_dwordx4 v125, s[12:13] offset:-512
	s_waitcnt lgkmcnt(4)
	v_mfma_f32_32x32x16_bf16 v[16:31], v[88:91], v[92:95], v[16:31]
	v_mfma_f32_32x32x16_bf16 v[0:15], v[88:91], v[96:99], v[0:15]
	ds_read_b128 v[84:87], v226
	ds_read_b128 v[92:95], v230
	ds_read_b128 v[96:99], v230 offset:4096
	ds_read_b128 v[88:91], v226 offset:4096
	s_add_i32 m0, s19, 0x1fb00
	s_waitcnt lgkmcnt(5)
	v_mfma_f32_32x32x16_bf16 v[48:63], v[102:105], v[110:113], v[48:63]
	global_load_lds_dwordx4 v124, s[14:15] offset:-512
	s_add_i32 m0, s19, 0x21b00
	v_mfma_f32_32x32x16_bf16 v[32:47], v[102:105], v[114:117], v[32:47]
	global_load_lds_dwordx4 v125, s[14:15] offset:-512
	s_waitcnt lgkmcnt(4)
	v_mfma_f32_32x32x16_bf16 v[16:31], v[106:109], v[110:113], v[16:31]
	v_mfma_f32_32x32x16_bf16 v[0:15], v[106:109], v[114:117], v[0:15]
	ds_read_b128 v[102:105], v227
	ds_read_b128 v[110:113], v231
	ds_read_b128 v[114:117], v231 offset:4096
	ds_read_b128 v[106:109], v227 offset:4096
	s_add_i32 m0, s19, 0x23b00
	s_waitcnt lgkmcnt(5)
	v_mfma_f32_32x32x16_bf16 v[48:63], v[84:87], v[92:95], v[48:63]
	global_load_lds_dwordx4 v126, s[14:15] offset:-512
	s_add_i32 m0, s19, 0x25b00
	v_mfma_f32_32x32x16_bf16 v[32:47], v[84:87], v[96:99], v[32:47]
	global_load_lds_dwordx4 v127, s[14:15] offset:-512
	s_waitcnt lgkmcnt(4)
	v_mfma_f32_32x32x16_bf16 v[16:31], v[88:91], v[92:95], v[16:31]
	v_mfma_f32_32x32x16_bf16 v[0:15], v[88:91], v[96:99], v[0:15]
	s_waitcnt lgkmcnt(0)
	s_waitcnt vmcnt(6)
	s_barrier
	ds_read_b128 v[84:87], v224 offset:49152
	ds_read_b128 v[92:95], v228 offset:49152
	ds_read_b128 v[96:99], v228 offset:53248
	ds_read_b128 v[88:91], v224 offset:53248
	v_mfma_f32_32x32x16_bf16 v[48:63], v[102:105], v[110:113], v[48:63]
	v_mfma_f32_32x32x16_bf16 v[32:47], v[102:105], v[114:117], v[32:47]
	v_mfma_f32_32x32x16_bf16 v[16:31], v[106:109], v[110:113], v[16:31]
	v_mfma_f32_32x32x16_bf16 v[0:15], v[106:109], v[114:117], v[0:15]
	ds_read_b128 v[102:105], v225 offset:49152
	ds_read_b128 v[110:113], v229 offset:49152
	ds_read_b128 v[114:117], v229 offset:53248
	ds_read_b128 v[106:109], v225 offset:53248
	s_add_i32 m0, s19, 0x280
	s_waitcnt lgkmcnt(5)
	v_mfma_f32_32x32x16_bf16 v[48:63], v[84:87], v[92:95], v[48:63]
	global_load_lds_dwordx4 v124, s[12:13] offset:-384
	s_add_i32 m0, s19, 0x2280
	v_mfma_f32_32x32x16_bf16 v[32:47], v[84:87], v[96:99], v[32:47]
	global_load_lds_dwordx4 v125, s[12:13] offset:-384
	s_waitcnt lgkmcnt(4)
	v_mfma_f32_32x32x16_bf16 v[16:31], v[88:91], v[92:95], v[16:31]
	v_mfma_f32_32x32x16_bf16 v[0:15], v[88:91], v[96:99], v[0:15]
	ds_read_b128 v[84:87], v226 offset:49152
	ds_read_b128 v[92:95], v230 offset:49152
	ds_read_b128 v[96:99], v230 offset:53248
	ds_read_b128 v[88:91], v226 offset:53248
	s_add_i32 m0, s19, 0x4280
	s_waitcnt lgkmcnt(5)
	v_mfma_f32_32x32x16_bf16 v[48:63], v[102:105], v[110:113], v[48:63]
	global_load_lds_dwordx4 v124, s[14:15] offset:-384
	s_add_i32 m0, s19, 0x6280
	v_mfma_f32_32x32x16_bf16 v[32:47], v[102:105], v[114:117], v[32:47]
	global_load_lds_dwordx4 v125, s[14:15] offset:-384
	s_waitcnt lgkmcnt(4)
	v_mfma_f32_32x32x16_bf16 v[16:31], v[106:109], v[110:113], v[16:31]
	v_mfma_f32_32x32x16_bf16 v[0:15], v[106:109], v[114:117], v[0:15]
	ds_read_b128 v[102:105], v227 offset:49152
	ds_read_b128 v[110:113], v231 offset:49152
	ds_read_b128 v[114:117], v231 offset:53248
	ds_read_b128 v[106:109], v227 offset:53248
	s_add_i32 m0, s19, 0x8280
	s_waitcnt lgkmcnt(5)
	v_mfma_f32_32x32x16_bf16 v[48:63], v[84:87], v[92:95], v[48:63]
	global_load_lds_dwordx4 v126, s[14:15] offset:-384
	s_add_i32 m0, s19, 0xa280
	v_mfma_f32_32x32x16_bf16 v[32:47], v[84:87], v[96:99], v[32:47]
	global_load_lds_dwordx4 v127, s[14:15] offset:-384
	s_waitcnt lgkmcnt(4)
	v_mfma_f32_32x32x16_bf16 v[16:31], v[88:91], v[92:95], v[16:31]
	v_mfma_f32_32x32x16_bf16 v[0:15], v[88:91], v[96:99], v[0:15]
	s_waitcnt lgkmcnt(0)
	s_waitcnt vmcnt(6)
	s_barrier
	ds_read_b128 v[84:87], v232
	ds_read_b128 v[92:95], v236
	ds_read_b128 v[96:99], v236 offset:4096
	ds_read_b128 v[88:91], v232 offset:4096
	v_mfma_f32_32x32x16_bf16 v[48:63], v[102:105], v[110:113], v[48:63]
	v_mfma_f32_32x32x16_bf16 v[32:47], v[102:105], v[114:117], v[32:47]
	v_mfma_f32_32x32x16_bf16 v[16:31], v[106:109], v[110:113], v[16:31]
	v_mfma_f32_32x32x16_bf16 v[0:15], v[106:109], v[114:117], v[0:15]
	ds_read_b128 v[102:105], v233
	ds_read_b128 v[110:113], v237
	ds_read_b128 v[114:117], v237 offset:4096
	ds_read_b128 v[106:109], v233 offset:4096
	s_add_i32 m0, s19, 0xc200
	s_waitcnt lgkmcnt(5)
	v_mfma_f32_32x32x16_bf16 v[48:63], v[84:87], v[92:95], v[48:63]
	global_load_lds_dwordx4 v124, s[12:13] offset:-256
	s_add_i32 m0, s19, 0xe200
	v_mfma_f32_32x32x16_bf16 v[32:47], v[84:87], v[96:99], v[32:47]
	global_load_lds_dwordx4 v125, s[12:13] offset:-256
	s_waitcnt lgkmcnt(4)
	v_mfma_f32_32x32x16_bf16 v[16:31], v[88:91], v[92:95], v[16:31]
	v_mfma_f32_32x32x16_bf16 v[0:15], v[88:91], v[96:99], v[0:15]
	ds_read_b128 v[84:87], v234
	ds_read_b128 v[92:95], v238
	ds_read_b128 v[96:99], v238 offset:4096
	ds_read_b128 v[88:91], v234 offset:4096
	s_add_i32 m0, s19, 0x10200
	s_waitcnt lgkmcnt(5)
	v_mfma_f32_32x32x16_bf16 v[48:63], v[102:105], v[110:113], v[48:63]
	global_load_lds_dwordx4 v124, s[14:15] offset:-256
	s_add_i32 m0, s19, 0x12200
	v_mfma_f32_32x32x16_bf16 v[32:47], v[102:105], v[114:117], v[32:47]
	global_load_lds_dwordx4 v125, s[14:15] offset:-256
	s_waitcnt lgkmcnt(4)
	v_mfma_f32_32x32x16_bf16 v[16:31], v[106:109], v[110:113], v[16:31]
	v_mfma_f32_32x32x16_bf16 v[0:15], v[106:109], v[114:117], v[0:15]
	ds_read_b128 v[102:105], v235
	ds_read_b128 v[110:113], v239
	ds_read_b128 v[114:117], v239 offset:4096
	ds_read_b128 v[106:109], v235 offset:4096
	s_add_i32 m0, s19, 0x14200
	s_waitcnt lgkmcnt(5)
	v_mfma_f32_32x32x16_bf16 v[48:63], v[84:87], v[92:95], v[48:63]
	global_load_lds_dwordx4 v126, s[14:15] offset:-256
	s_add_i32 m0, s19, 0x16200
	v_mfma_f32_32x32x16_bf16 v[32:47], v[84:87], v[96:99], v[32:47]
	global_load_lds_dwordx4 v127, s[14:15] offset:-256
	s_waitcnt lgkmcnt(4)
	v_mfma_f32_32x32x16_bf16 v[16:31], v[88:91], v[92:95], v[16:31]
	v_mfma_f32_32x32x16_bf16 v[0:15], v[88:91], v[96:99], v[0:15]
	s_waitcnt lgkmcnt(0)
	s_waitcnt vmcnt(6)
	s_barrier
	ds_read_b128 v[84:87], v224
	ds_read_b128 v[92:95], v228
	ds_read_b128 v[96:99], v228 offset:4096
	ds_read_b128 v[88:91], v224 offset:4096
	v_mfma_f32_32x32x16_bf16 v[48:63], v[102:105], v[110:113], v[48:63]
	v_mfma_f32_32x32x16_bf16 v[32:47], v[102:105], v[114:117], v[32:47]
	v_mfma_f32_32x32x16_bf16 v[16:31], v[106:109], v[110:113], v[16:31]
	v_mfma_f32_32x32x16_bf16 v[0:15], v[106:109], v[114:117], v[0:15]
	ds_read_b128 v[102:105], v225
	ds_read_b128 v[110:113], v229
	ds_read_b128 v[114:117], v229 offset:4096
	ds_read_b128 v[106:109], v225 offset:4096
	s_add_i32 m0, s19, 0x1b980
	s_waitcnt lgkmcnt(5)
	v_mfma_f32_32x32x16_bf16 v[48:63], v[84:87], v[92:95], v[48:63]
	global_load_lds_dwordx4 v124, s[12:13] offset:-128
	s_add_i32 m0, s19, 0x1d980
	v_mfma_f32_32x32x16_bf16 v[32:47], v[84:87], v[96:99], v[32:47]
	global_load_lds_dwordx4 v125, s[12:13] offset:-128
	s_waitcnt lgkmcnt(4)
	v_mfma_f32_32x32x16_bf16 v[16:31], v[88:91], v[92:95], v[16:31]
	v_mfma_f32_32x32x16_bf16 v[0:15], v[88:91], v[96:99], v[0:15]
	ds_read_b128 v[84:87], v226
	ds_read_b128 v[92:95], v230
	ds_read_b128 v[96:99], v230 offset:4096
	ds_read_b128 v[88:91], v226 offset:4096
	s_add_i32 m0, s19, 0x1f980
	s_waitcnt lgkmcnt(5)
	v_mfma_f32_32x32x16_bf16 v[48:63], v[102:105], v[110:113], v[48:63]
	global_load_lds_dwordx4 v124, s[14:15] offset:-128
	s_add_i32 m0, s19, 0x21980
	v_mfma_f32_32x32x16_bf16 v[32:47], v[102:105], v[114:117], v[32:47]
	global_load_lds_dwordx4 v125, s[14:15] offset:-128
	s_waitcnt lgkmcnt(4)
	v_mfma_f32_32x32x16_bf16 v[16:31], v[106:109], v[110:113], v[16:31]
	v_mfma_f32_32x32x16_bf16 v[0:15], v[106:109], v[114:117], v[0:15]
	ds_read_b128 v[102:105], v227
	ds_read_b128 v[110:113], v231
	ds_read_b128 v[114:117], v231 offset:4096
	ds_read_b128 v[106:109], v227 offset:4096
	s_add_i32 m0, s19, 0x23980
	s_waitcnt lgkmcnt(5)
	v_mfma_f32_32x32x16_bf16 v[48:63], v[84:87], v[92:95], v[48:63]
	global_load_lds_dwordx4 v126, s[14:15] offset:-128
	s_add_i32 m0, s19, 0x25980
	v_mfma_f32_32x32x16_bf16 v[32:47], v[84:87], v[96:99], v[32:47]
	global_load_lds_dwordx4 v127, s[14:15] offset:-128
	s_waitcnt lgkmcnt(4)
	v_mfma_f32_32x32x16_bf16 v[16:31], v[88:91], v[92:95], v[16:31]
	v_mfma_f32_32x32x16_bf16 v[0:15], v[88:91], v[96:99], v[0:15]
	s_waitcnt lgkmcnt(0)
	s_waitcnt vmcnt(6)
	s_barrier
	ds_read_b128 v[84:87], v224 offset:49152
	ds_read_b128 v[92:95], v228 offset:49152
	ds_read_b128 v[96:99], v228 offset:53248
	ds_read_b128 v[88:91], v224 offset:53248
	v_mfma_f32_32x32x16_bf16 v[48:63], v[102:105], v[110:113], v[48:63]
	v_mfma_f32_32x32x16_bf16 v[32:47], v[102:105], v[114:117], v[32:47]
	v_mfma_f32_32x32x16_bf16 v[16:31], v[106:109], v[110:113], v[16:31]
	v_mfma_f32_32x32x16_bf16 v[0:15], v[106:109], v[114:117], v[0:15]
	ds_read_b128 v[102:105], v225 offset:49152
	ds_read_b128 v[110:113], v229 offset:49152
	ds_read_b128 v[114:117], v229 offset:53248
	ds_read_b128 v[106:109], v225 offset:53248
	s_add_i32 m0, s19, 0x100
	s_waitcnt lgkmcnt(5)
	v_mfma_f32_32x32x16_bf16 v[48:63], v[84:87], v[92:95], v[48:63]
	global_load_lds_dwordx4 v124, s[12:13]
	s_add_i32 m0, s19, 0x2100
	v_mfma_f32_32x32x16_bf16 v[32:47], v[84:87], v[96:99], v[32:47]
	global_load_lds_dwordx4 v125, s[12:13]
	s_waitcnt lgkmcnt(4)
	v_mfma_f32_32x32x16_bf16 v[16:31], v[88:91], v[92:95], v[16:31]
	v_mfma_f32_32x32x16_bf16 v[0:15], v[88:91], v[96:99], v[0:15]
	ds_read_b128 v[84:87], v226 offset:49152
	ds_read_b128 v[92:95], v230 offset:49152
	ds_read_b128 v[96:99], v230 offset:53248
	ds_read_b128 v[88:91], v226 offset:53248
	s_add_i32 m0, s19, 0x4100
	s_waitcnt lgkmcnt(5)
	v_mfma_f32_32x32x16_bf16 v[48:63], v[102:105], v[110:113], v[48:63]
	global_load_lds_dwordx4 v124, s[14:15]
	s_add_i32 m0, s19, 0x6100
	v_mfma_f32_32x32x16_bf16 v[32:47], v[102:105], v[114:117], v[32:47]
	global_load_lds_dwordx4 v125, s[14:15]
	s_waitcnt lgkmcnt(4)
	v_mfma_f32_32x32x16_bf16 v[16:31], v[106:109], v[110:113], v[16:31]
	v_mfma_f32_32x32x16_bf16 v[0:15], v[106:109], v[114:117], v[0:15]
	ds_read_b128 v[102:105], v227 offset:49152
	ds_read_b128 v[110:113], v231 offset:49152
	ds_read_b128 v[114:117], v231 offset:53248
	ds_read_b128 v[106:109], v227 offset:53248
	s_add_i32 m0, s19, 0x8100
	s_waitcnt lgkmcnt(5)
	v_mfma_f32_32x32x16_bf16 v[48:63], v[84:87], v[92:95], v[48:63]
	global_load_lds_dwordx4 v126, s[14:15]
	s_add_i32 m0, s19, 0xa100
	v_mfma_f32_32x32x16_bf16 v[32:47], v[84:87], v[96:99], v[32:47]
	global_load_lds_dwordx4 v127, s[14:15]
	s_waitcnt lgkmcnt(4)
	v_mfma_f32_32x32x16_bf16 v[16:31], v[88:91], v[92:95], v[16:31]
	v_mfma_f32_32x32x16_bf16 v[0:15], v[88:91], v[96:99], v[0:15]
	s_waitcnt lgkmcnt(0)
	s_waitcnt vmcnt(6)
	s_barrier
	ds_read_b128 v[84:87], v232
	ds_read_b128 v[92:95], v236
	ds_read_b128 v[96:99], v236 offset:4096
	ds_read_b128 v[88:91], v232 offset:4096
	v_mfma_f32_32x32x16_bf16 v[48:63], v[102:105], v[110:113], v[48:63]
	v_mfma_f32_32x32x16_bf16 v[32:47], v[102:105], v[114:117], v[32:47]
	v_mfma_f32_32x32x16_bf16 v[16:31], v[106:109], v[110:113], v[16:31]
	v_mfma_f32_32x32x16_bf16 v[0:15], v[106:109], v[114:117], v[0:15]
	ds_read_b128 v[102:105], v233
	ds_read_b128 v[110:113], v237
	ds_read_b128 v[114:117], v237 offset:4096
	ds_read_b128 v[106:109], v233 offset:4096
	s_waitcnt lgkmcnt(5)
	v_mfma_f32_32x32x16_bf16 v[48:63], v[84:87], v[92:95], v[48:63]
	v_mfma_f32_32x32x16_bf16 v[32:47], v[84:87], v[96:99], v[32:47]
	s_waitcnt lgkmcnt(4)
	v_mfma_f32_32x32x16_bf16 v[16:31], v[88:91], v[92:95], v[16:31]
	v_mfma_f32_32x32x16_bf16 v[0:15], v[88:91], v[96:99], v[0:15]
	ds_read_b128 v[84:87], v234
	ds_read_b128 v[92:95], v238
	ds_read_b128 v[96:99], v238 offset:4096
	ds_read_b128 v[88:91], v234 offset:4096
	s_waitcnt lgkmcnt(5)
	v_mfma_f32_32x32x16_bf16 v[48:63], v[102:105], v[110:113], v[48:63]
	v_mfma_f32_32x32x16_bf16 v[32:47], v[102:105], v[114:117], v[32:47]
	s_waitcnt lgkmcnt(4)
	v_mfma_f32_32x32x16_bf16 v[16:31], v[106:109], v[110:113], v[16:31]
	v_mfma_f32_32x32x16_bf16 v[0:15], v[106:109], v[114:117], v[0:15]
	ds_read_b128 v[102:105], v235
	ds_read_b128 v[110:113], v239
	ds_read_b128 v[114:117], v239 offset:4096
	ds_read_b128 v[106:109], v235 offset:4096
	s_waitcnt lgkmcnt(5)
	v_mfma_f32_32x32x16_bf16 v[48:63], v[84:87], v[92:95], v[48:63]
	v_mfma_f32_32x32x16_bf16 v[32:47], v[84:87], v[96:99], v[32:47]
	s_waitcnt lgkmcnt(4)
	v_mfma_f32_32x32x16_bf16 v[16:31], v[88:91], v[92:95], v[16:31]
	v_mfma_f32_32x32x16_bf16 v[0:15], v[88:91], v[96:99], v[0:15]
	s_waitcnt lgkmcnt(0)
	s_waitcnt vmcnt(0)
	s_barrier
	ds_read_b128 v[84:87], v224
	ds_read_b128 v[92:95], v228
	ds_read_b128 v[96:99], v228 offset:4096
	ds_read_b128 v[88:91], v224 offset:4096
	v_mfma_f32_32x32x16_bf16 v[48:63], v[102:105], v[110:113], v[48:63]
	v_mfma_f32_32x32x16_bf16 v[32:47], v[102:105], v[114:117], v[32:47]
	v_mfma_f32_32x32x16_bf16 v[16:31], v[106:109], v[110:113], v[16:31]
	v_mfma_f32_32x32x16_bf16 v[0:15], v[106:109], v[114:117], v[0:15]
	ds_read_b128 v[102:105], v225
	ds_read_b128 v[110:113], v229
	ds_read_b128 v[114:117], v229 offset:4096
	ds_read_b128 v[106:109], v225 offset:4096
	s_waitcnt lgkmcnt(5)
	v_mfma_f32_32x32x16_bf16 v[48:63], v[84:87], v[92:95], v[48:63]
	v_mfma_f32_32x32x16_bf16 v[32:47], v[84:87], v[96:99], v[32:47]
	s_waitcnt lgkmcnt(4)
	v_mfma_f32_32x32x16_bf16 v[16:31], v[88:91], v[92:95], v[16:31]
	v_mfma_f32_32x32x16_bf16 v[0:15], v[88:91], v[96:99], v[0:15]
	ds_read_b128 v[84:87], v226
	ds_read_b128 v[92:95], v230
	ds_read_b128 v[96:99], v230 offset:4096
	ds_read_b128 v[88:91], v226 offset:4096
	s_waitcnt lgkmcnt(5)
	v_mfma_f32_32x32x16_bf16 v[48:63], v[102:105], v[110:113], v[48:63]
	v_mfma_f32_32x32x16_bf16 v[32:47], v[102:105], v[114:117], v[32:47]
	s_waitcnt lgkmcnt(4)
	v_mfma_f32_32x32x16_bf16 v[16:31], v[106:109], v[110:113], v[16:31]
	v_mfma_f32_32x32x16_bf16 v[0:15], v[106:109], v[114:117], v[0:15]
	ds_read_b128 v[102:105], v227
	ds_read_b128 v[110:113], v231
	ds_read_b128 v[114:117], v231 offset:4096
	ds_read_b128 v[106:109], v227 offset:4096
	s_waitcnt lgkmcnt(5)
	v_mfma_f32_32x32x16_bf16 v[48:63], v[84:87], v[92:95], v[48:63]
	v_mfma_f32_32x32x16_bf16 v[32:47], v[84:87], v[96:99], v[32:47]
	s_waitcnt lgkmcnt(4)
	v_mfma_f32_32x32x16_bf16 v[16:31], v[88:91], v[92:95], v[16:31]
	v_mfma_f32_32x32x16_bf16 v[0:15], v[88:91], v[96:99], v[0:15]
	s_waitcnt lgkmcnt(0)
	s_waitcnt vmcnt(0)
	s_barrier
.Lg2_done:
	v_mfma_f32_32x32x16_bf16 v[48:63], v[102:105], v[110:113], v[48:63]
	v_mfma_f32_32x32x16_bf16 v[32:47], v[102:105], v[114:117], v[32:47]
	v_mfma_f32_32x32x16_bf16 v[16:31], v[106:109], v[110:113], v[16:31]
	v_mfma_f32_32x32x16_bf16 v[0:15], v[106:109], v[114:117], v[0:15]
	s_nop 7
	s_nop 3
	ds_write_b32 v240, v48
	ds_write_b32 v240, v49 offset:272
	ds_write_b32 v240, v50 offset:544
	ds_write_b32 v240, v51 offset:816
	ds_write_b32 v240, v52 offset:2176
	ds_write_b32 v240, v53 offset:2448
	ds_write_b32 v240, v54 offset:2720
	ds_write_b32 v240, v55 offset:2992
	ds_write_b32 v240, v56 offset:4352
	ds_write_b32 v240, v57 offset:4624
	ds_write_b32 v240, v58 offset:4896
	ds_write_b32 v240, v59 offset:5168
	ds_write_b32 v240, v60 offset:6528
	ds_write_b32 v240, v61 offset:6800
	ds_write_b32 v240, v62 offset:7072
	ds_write_b32 v240, v63 offset:7344
	ds_write_b32 v240, v32 offset:128
	ds_write_b32 v240, v33 offset:400
	ds_write_b32 v240, v34 offset:672
	ds_write_b32 v240, v35 offset:944
	ds_write_b32 v240, v36 offset:2304
	ds_write_b32 v240, v37 offset:2576
	ds_write_b32 v240, v38 offset:2848
	ds_write_b32 v240, v39 offset:3120
	ds_write_b32 v240, v40 offset:4480
	ds_write_b32 v240, v41 offset:4752
	ds_write_b32 v240, v42 offset:5024
	ds_write_b32 v240, v43 offset:5296
	ds_write_b32 v240, v44 offset:6656
	ds_write_b32 v240, v45 offset:6928
	ds_write_b32 v240, v46 offset:7200
	ds_write_b32 v240, v47 offset:7472
	ds_read_b128 v[224:227], v83
	ds_read_b128 v[228:231], v83 offset:1088
	ds_read_b128 v[232:235], v83 offset:2176
	ds_read_b128 v[236:239], v83 offset:3264
	s_waitcnt lgkmcnt(3)
	v_pk_fma_f32 v[130:131], v[66:67], v[226:227], v[130:131]
	v_pk_fma_f32 v[128:129], v[64:65], v[224:225], v[128:129]
	global_store_dwordx4 v216, v[128:131], s[24:25]
	s_waitcnt lgkmcnt(2)
	v_pk_fma_f32 v[134:135], v[66:67], v[230:231], v[134:135]
	v_pk_fma_f32 v[132:133], v[64:65], v[228:229], v[132:133]
	global_store_dwordx4 v217, v[132:135], s[24:25]
	s_waitcnt lgkmcnt(1)
	v_pk_fma_f32 v[138:139], v[66:67], v[234:235], v[138:139]
	v_pk_fma_f32 v[136:137], v[64:65], v[232:233], v[136:137]
	global_store_dwordx4 v218, v[136:139], s[24:25]
	s_waitcnt lgkmcnt(0)
	v_pk_fma_f32 v[142:143], v[66:67], v[238:239], v[142:143]
	v_pk_fma_f32 v[140:141], v[64:65], v[236:237], v[140:141]
	global_store_dwordx4 v219, v[140:143], s[24:25]
	ds_read_b128 v[224:227], v83 offset:4352
	ds_read_b128 v[228:231], v83 offset:5440
	ds_read_b128 v[232:235], v83 offset:6528
	ds_read_b128 v[236:239], v83 offset:7616
	s_waitcnt lgkmcnt(3)
	v_pk_fma_f32 v[146:147], v[66:67], v[226:227], v[146:147]
	v_pk_fma_f32 v[144:145], v[64:65], v[224:225], v[144:145]
	global_store_dwordx4 v220, v[144:147], s[24:25]
	s_waitcnt lgkmcnt(2)
	v_pk_fma_f32 v[150:151], v[66:67], v[230:231], v[150:151]
	v_pk_fma_f32 v[148:149], v[64:65], v[228:229], v[148:149]
	global_store_dwordx4 v221, v[148:151], s[24:25]
	s_waitcnt lgkmcnt(1)
	v_pk_fma_f32 v[154:155], v[66:67], v[234:235], v[154:155]
	v_pk_fma_f32 v[152:153], v[64:65], v[232:233], v[152:153]
	global_store_dwordx4 v222, v[152:155], s[24:25]
	s_waitcnt lgkmcnt(0)
	v_pk_fma_f32 v[158:159], v[66:67], v[238:239], v[158:159]
	v_pk_fma_f32 v[156:157], v[64:65], v[236:237], v[156:157]
	global_store_dwordx4 v223, v[156:159], s[24:25]
	ds_write_b32 v240, v16
	ds_write_b32 v240, v17 offset:272
	ds_write_b32 v240, v18 offset:544
	ds_write_b32 v240, v19 offset:816
	ds_write_b32 v240, v20 offset:2176
	ds_write_b32 v240, v21 offset:2448
	ds_write_b32 v240, v22 offset:2720
	ds_write_b32 v240, v23 offset:2992
	ds_write_b32 v240, v24 offset:4352
	ds_write_b32 v240, v25 offset:4624
	ds_write_b32 v240, v26 offset:4896
	ds_write_b32 v240, v27 offset:5168
	ds_write_b32 v240, v28 offset:6528
	ds_write_b32 v240, v29 offset:6800
	ds_write_b32 v240, v30 offset:7072
	ds_write_b32 v240, v31 offset:7344
	ds_write_b32 v240, v0 offset:128
	ds_write_b32 v240, v1 offset:400
	ds_write_b32 v240, v2 offset:672
	ds_write_b32 v240, v3 offset:944
	ds_write_b32 v240, v4 offset:2304
	ds_write_b32 v240, v5 offset:2576
	ds_write_b32 v240, v6 offset:2848
	ds_write_b32 v240, v7 offset:3120
	ds_write_b32 v240, v8 offset:4480
	ds_write_b32 v240, v9 offset:4752
	ds_write_b32 v240, v10 offset:5024
	ds_write_b32 v240, v11 offset:5296
	ds_write_b32 v240, v12 offset:6656
	ds_write_b32 v240, v13 offset:6928
	ds_write_b32 v240, v14 offset:7200
	ds_write_b32 v240, v15 offset:7472
	ds_read_b128 v[224:227], v83
	ds_read_b128 v[228:231], v83 offset:1088
	ds_read_b128 v[232:235], v83 offset:2176
	ds_read_b128 v[236:239], v83 offset:3264
	s_waitcnt lgkmcnt(3)
	v_pk_fma_f32 v[162:163], v[66:67], v[226:227], v[162:163]
	v_pk_fma_f32 v[160:161], v[64:65], v[224:225], v[160:161]
	global_store_dwordx4 v216, v[160:163], s[10:11]
	s_waitcnt lgkmcnt(2)
	v_pk_fma_f32 v[166:167], v[66:67], v[230:231], v[166:167]
	v_pk_fma_f32 v[164:165], v[64:65], v[228:229], v[164:165]
	global_store_dwordx4 v217, v[164:167], s[10:11]
	s_waitcnt lgkmcnt(1)
	v_pk_fma_f32 v[170:171], v[66:67], v[234:235], v[170:171]
	v_pk_fma_f32 v[168:169], v[64:65], v[232:233], v[168:169]
	global_store_dwordx4 v218, v[168:171], s[10:11]
	s_waitcnt lgkmcnt(0)
	v_pk_fma_f32 v[174:175], v[66:67], v[238:239], v[174:175]
	v_pk_fma_f32 v[172:173], v[64:65], v[236:237], v[172:173]
	global_store_dwordx4 v219, v[172:175], s[10:11]
	ds_read_b128 v[224:227], v83 offset:4352
	ds_read_b128 v[228:231], v83 offset:5440
	ds_read_b128 v[232:235], v83 offset:6528
	ds_read_b128 v[236:239], v83 offset:7616
	s_waitcnt lgkmcnt(3)
	v_pk_fma_f32 v[178:179], v[66:67], v[226:227], v[178:179]
	v_pk_fma_f32 v[176:177], v[64:65], v[224:225], v[176:177]
	global_store_dwordx4 v220, v[176:179], s[10:11]
	s_waitcnt lgkmcnt(2)
	v_pk_fma_f32 v[182:183], v[66:67], v[230:231], v[182:183]
	v_pk_fma_f32 v[180:181], v[64:65], v[228:229], v[180:181]
	global_store_dwordx4 v221, v[180:183], s[10:11]
	s_waitcnt lgkmcnt(1)
	v_pk_fma_f32 v[192:193], v[66:67], v[234:235], v[192:193]
	v_pk_fma_f32 v[190:191], v[64:65], v[232:233], v[190:191]
	global_store_dwordx4 v222, v[190:193], s[10:11]
	s_waitcnt lgkmcnt(0)
	v_pk_fma_f32 v[196:197], v[66:67], v[238:239], v[196:197]
	v_pk_fma_f32 v[194:195], v[64:65], v[236:237], v[194:195]
	global_store_dwordx4 v223, v[194:197], s[10:11]
	s_add_i32 s47, s47, s86
	s_cmp_ge_i32 s47, s3
	s_barrier
	s_cbranch_scc0 .LBB0_868
